# v26 + LN1 router: row reductions and lane reads of the expert accumulators run only for the selected group (behind the group decision) instead of for all four groups
# speedup vs baseline: 1.0034x; 1.0034x over previous
.LBB0_552:
	s_add_i32 s23, s7, 1
	s_waitcnt vmcnt(0)
	v_mov_b64_e32 v[38:39], v[84:85]
	v_mov_b64_e32 v[32:33], v[92:93]
	v_mov_b64_e32 v[34:35], v[90:91]
	v_mov_b64_e32 v[36:37], v[88:89]
	v_mov_b32_e32 v0, s23
	v_min_u32_e32 v0, 15, v0
	v_mov_b32_e32 v1, 0
	v_lshl_add_u64 v[0:1], v[82:83], 0, v[0:1]
	v_lshlrev_b64 v[2:3], 12, v[0:1]
	v_lshlrev_b64 v[0:1], 11, v[0:1]
	v_lshl_add_u64 v[12:13], v[62:63], 0, v[2:3]
	v_lshl_add_u64 v[92:93], v[64:65], 0, v[0:1]
	global_load_dwordx4 v[0:3], v[12:13], off nt
	global_load_dwordx2 v[84:85], v[92:93], off nt
	global_load_dwordx4 v[4:7], v[12:13], off offset:1024 nt
	global_load_dwordx2 v[88:89], v[92:93], off offset:512 nt
	global_load_dwordx4 v[8:11], v[12:13], off offset:2048 nt
	global_load_dwordx2 v[90:91], v[92:93], off offset:1024 nt
	s_nop 0
	global_load_dwordx4 v[12:15], v[12:13], off offset:3072 nt
	s_nop 0
	global_load_dwordx2 v[92:93], v[92:93], off offset:1536 nt
	v_lshlrev_b32_e32 v40, 16, v38
	v_and_b32_e32 v41, 0xffff0000, v38
	v_lshlrev_b32_e32 v38, 16, v39
	v_and_b32_e32 v39, 0xffff0000, v39
	v_lshlrev_b32_e32 v54, 16, v36
	v_and_b32_e32 v55, 0xffff0000, v36
	v_lshlrev_b32_e32 v94, 16, v37
	v_and_b32_e32 v95, 0xffff0000, v37
	v_lshlrev_b32_e32 v96, 16, v34
	v_and_b32_e32 v97, 0xffff0000, v34
	v_lshlrev_b32_e32 v100, 16, v35
	v_and_b32_e32 v101, 0xffff0000, v35
	v_lshlrev_b32_e32 v102, 16, v32
	v_and_b32_e32 v103, 0xffff0000, v32
	v_lshlrev_b32_e32 v104, 16, v33
	v_and_b32_e32 v105, 0xffff0000, v33
	v_pk_fma_f32 v[106:107], v[30:31], s[22:23], v[38:39] op_sel_hi:[1,0,1]
	ds_read_b128 v[30:33], v234
	ds_read_b128 v[34:37], v234 offset:4096
	v_pk_fma_f32 v[28:29], v[28:29], s[22:23], v[40:41] op_sel_hi:[1,0,1]
	v_pk_fma_f32 v[20:21], v[20:21], s[22:23], v[54:55] op_sel_hi:[1,0,1]
	v_add_f32_e32 v38, v28, v29
	v_add_f32_e32 v38, v38, v106
	v_pk_fma_f32 v[22:23], v[22:23], s[22:23], v[94:95] op_sel_hi:[1,0,1]
	v_add_f32_e32 v54, v20, v21
	v_pk_fma_f32 v[24:25], v[24:25], s[22:23], v[96:97] op_sel_hi:[1,0,1]
	v_add_f32_e32 v38, v107, v38
	v_add_f32_e32 v54, v54, v22
	v_pk_fma_f32 v[26:27], v[26:27], s[22:23], v[100:101] op_sel_hi:[1,0,1]
	v_add_f32_e32 v55, v24, v25
	v_add_f32_e32 v98, 0, v38
	v_add_f32_e32 v54, v23, v54
	v_add_f32_e32 v55, v55, v26
	v_add_f32_e32 v54, v98, v54
	v_add_f32_e32 v55, v27, v55
	v_pk_fma_f32 v[16:17], v[16:17], s[22:23], v[102:103] op_sel_hi:[1,0,1]
	v_add_f32_e32 v54, v54, v55
	v_pk_fma_f32 v[18:19], v[18:19], s[22:23], v[104:105] op_sel_hi:[1,0,1]
	v_add_f32_e32 v55, v16, v17
	v_add_f32_e32 v55, v55, v18
	v_add_f32_e32 v55, v19, v55
	v_add_f32_e32 v54, v54, v55
	ds_read_b128 v[38:41], v60
	ds_read_b128 v[42:45], v60 offset:4096
	ds_read_b128 v[46:49], v60 offset:8192
	ds_read_b128 v[50:53], v60 offset:12288
	ds_read_b128 v[108:111], v60 offset:16384
	ds_read_b128 v[122:125], v60 offset:20480
	ds_read_b128 v[130:133], v60 offset:24576
	ds_read_b128 v[134:137], v60 offset:28672
	ds_read_b128 v[138:141], v60 offset:32768
	ds_read_b128 v[142:145], v60 offset:36864
	ds_read_b128 v[146:149], v60 offset:40960
	ds_read_b128 v[150:153], v60 offset:45056
	ds_read_b128 v[154:157], v60 offset:49152
	v_add_f32_dpp v54, v54, v54 quad_perm:[1,0,3,2] row_mask:0xf bank_mask:0xf bound_ctrl:1
	s_nop 1
	v_add_f32_dpp v54, v54, v54 quad_perm:[2,3,0,1] row_mask:0xf bank_mask:0xf bound_ctrl:1
	s_nop 1
	v_add_f32_dpp v54, v54, v54 row_half_mirror row_mask:0xf bank_mask:0xf bound_ctrl:1
	s_nop 1
	v_add_f32_dpp v54, v54, v54 row_mirror row_mask:0xf bank_mask:0xf bound_ctrl:1
	s_nop 0
	v_readlane_b32 s2, v54, 16
	v_readlane_b32 s4, v54, 48
	v_readlane_b32 s0, v54, 0
	v_readlane_b32 s1, v54, 32
	v_mov_b32_e32 v54, s2
	v_mov_b32_e32 v55, s4
	v_pk_add_f32 v[54:55], s[0:1], v[54:55]
	s_nop 0
	v_add_f32_e32 v54, v54, v55
	v_mul_f32_e32 v54, 0x3a800000, v54
	v_pk_add_f32 v[28:29], v[28:29], v[54:55] op_sel_hi:[1,0] neg_lo:[0,1] neg_hi:[0,1]
	v_pk_add_f32 v[126:127], v[106:107], v[54:55] op_sel_hi:[1,0] neg_lo:[0,1] neg_hi:[0,1]
	v_pk_mul_f32 v[104:105], v[28:29], v[28:29]
	v_pk_mul_f32 v[106:107], v[126:127], v[126:127]
	v_pk_add_f32 v[158:159], v[20:21], v[54:55] op_sel_hi:[1,0] neg_lo:[0,1] neg_hi:[0,1]
	v_pk_add_f32 v[160:161], v[22:23], v[54:55] op_sel_hi:[1,0] neg_lo:[0,1] neg_hi:[0,1]
	v_pk_add_f32 v[100:101], v[24:25], v[54:55] op_sel_hi:[1,0] neg_lo:[0,1] neg_hi:[0,1]
	v_pk_add_f32 v[102:103], v[26:27], v[54:55] op_sel_hi:[1,0] neg_lo:[0,1] neg_hi:[0,1]
	v_pk_add_f32 v[94:95], v[16:17], v[54:55] op_sel_hi:[1,0] neg_lo:[0,1] neg_hi:[0,1]
	v_pk_add_f32 v[96:97], v[18:19], v[54:55] op_sel_hi:[1,0] neg_lo:[0,1] neg_hi:[0,1]
	v_add_f32_e32 v54, v104, v105
	v_add_f32_e32 v54, v106, v54
	v_pk_mul_f32 v[20:21], v[158:159], v[158:159]
	v_add_f32_e32 v54, v107, v54
	v_add_f32_e32 v20, v20, v54
	v_pk_mul_f32 v[22:23], v[160:161], v[160:161]
	v_add_f32_e32 v20, v21, v20
	v_add_f32_e32 v20, v22, v20
	v_pk_mul_f32 v[24:25], v[100:101], v[100:101]
	v_add_f32_e32 v20, v23, v20
	v_add_f32_e32 v20, v24, v20
	v_pk_mul_f32 v[26:27], v[102:103], v[102:103]
	v_add_f32_e32 v20, v25, v20
	v_add_f32_e32 v20, v26, v20
	v_pk_mul_f32 v[16:17], v[94:95], v[94:95]
	v_add_f32_e32 v20, v27, v20
	v_add_f32_e32 v16, v16, v20
	v_pk_mul_f32 v[18:19], v[96:97], v[96:97]
	v_add_f32_e32 v16, v17, v16
	v_add_f32_e32 v16, v18, v16
	v_add_f32_e32 v16, v19, v16
	s_nop 1
	v_add_f32_dpp v16, v16, v16 quad_perm:[1,0,3,2] row_mask:0xf bank_mask:0xf bound_ctrl:1
	s_nop 1
	v_add_f32_dpp v16, v16, v16 quad_perm:[2,3,0,1] row_mask:0xf bank_mask:0xf bound_ctrl:1
	s_nop 1
	v_add_f32_dpp v16, v16, v16 row_half_mirror row_mask:0xf bank_mask:0xf bound_ctrl:1
	s_nop 1
	v_add_f32_dpp v16, v16, v16 row_mirror row_mask:0xf bank_mask:0xf bound_ctrl:1
	s_nop 0
	v_readlane_b32 s2, v16, 16
	v_readlane_b32 s4, v16, 48
	v_readlane_b32 s0, v16, 0
	v_readlane_b32 s1, v16, 32
	v_mov_b32_e32 v16, s2
	v_mov_b32_e32 v17, s4
	v_pk_add_f32 v[16:17], s[0:1], v[16:17]
	s_mov_b32 s0, 0x800000
	v_add_f32_e32 v16, v16, v17
	v_fmamk_f32 v16, v16, 0x3a800000, v116
	v_cmp_gt_f32_e32 vcc, s0, v16
	v_mul_f32_e32 v17, 0x4b800000, v16
	s_nop 0
	v_cndmask_b32_e32 v16, v16, v17, vcc
	v_rsq_f32_e32 v54, v16
	ds_read_b128 v[16:19], v60 offset:53248
	s_waitcnt lgkmcnt(15)
	ds_read_b128 v[20:23], v60 offset:57344
	s_waitcnt lgkmcnt(15)
	ds_read_b128 v[24:27], v60 offset:61440
	s_waitcnt lgkmcnt(15)
	v_mul_f32_e32 v55, 0x45800000, v54
	v_cndmask_b32_e32 v98, v54, v55, vcc
	v_pk_mul_f32 v[28:29], v[28:29], v[98:99] op_sel_hi:[1,0]
	v_pk_fma_f32 v[106:107], v[30:31], v[28:29], v[34:35]
	v_pk_mul_f32 v[28:29], v[126:127], v[98:99] op_sel_hi:[1,0]
	s_waitcnt lgkmcnt(2)
	v_mul_f32_e32 v17, v107, v17
	v_pk_fma_f32 v[104:105], v[32:33], v[28:29], v[36:37]
	v_cvt_pk_bf16_f32 v28, v106, v107
	v_cvt_pk_bf16_f32 v29, v104, v105
	global_store_dwordx2 v[86:87], v[28:29], off offset:-1024
	v_mul_f32_e32 v54, v39, v107
	v_fmac_f32_e32 v54, v38, v106
	ds_read_b128 v[32:35], v234 offset:1024
	ds_read_b128 v[36:39], v234 offset:5120
	v_fmac_f32_e32 v54, v104, v40
	v_fmac_f32_e32 v54, v105, v41
	v_mul_f32_e32 v55, v107, v43
	v_fmac_f32_e32 v55, v106, v42
	v_fmac_f32_e32 v55, v104, v44
	v_fmac_f32_e32 v55, v105, v45
	v_mul_f32_e32 v28, v107, v47
	v_fmac_f32_e32 v28, v106, v46
	v_fmac_f32_e32 v28, v104, v48
	v_fmac_f32_e32 v28, v105, v49
	v_add_f32_e32 v46, 0, v28
	v_mul_f32_e32 v45, v107, v51
	v_fmac_f32_e32 v45, v106, v50
	v_fmac_f32_e32 v45, v104, v52
	v_fmac_f32_e32 v45, v105, v53
	v_mul_f32_e32 v44, v107, v109
	v_fmac_f32_e32 v44, v106, v108
	v_fmac_f32_e32 v44, v104, v110
	v_fmac_f32_e32 v44, v105, v111
	v_mul_f32_e32 v53, v107, v123
	v_fmac_f32_e32 v53, v106, v122
	v_fmac_f32_e32 v53, v104, v124
	v_fmac_f32_e32 v53, v105, v125
	v_mul_f32_e32 v52, v107, v131
	v_fmac_f32_e32 v52, v106, v130
	v_fmac_f32_e32 v52, v104, v132
	v_fmac_f32_e32 v52, v105, v133
	v_mul_f32_e32 v51, v107, v135
	v_fmac_f32_e32 v51, v106, v134
	v_fmac_f32_e32 v51, v104, v136
	v_fmac_f32_e32 v51, v105, v137
	v_mul_f32_e32 v50, v107, v139
	v_fmac_f32_e32 v50, v106, v138
	v_fmac_f32_e32 v50, v104, v140
	v_fmac_f32_e32 v50, v105, v141
	v_mul_f32_e32 v49, v107, v143
	v_fmac_f32_e32 v49, v106, v142
	v_fmac_f32_e32 v49, v104, v144
	v_fmac_f32_e32 v49, v105, v145
	v_mul_f32_e32 v48, v107, v147
	v_fmac_f32_e32 v48, v106, v146
	v_fmac_f32_e32 v48, v104, v148
	v_fmac_f32_e32 v48, v105, v149
	v_mul_f32_e32 v131, v107, v151
	v_fmac_f32_e32 v17, v106, v16
	s_waitcnt lgkmcnt(3)
	v_mul_f32_e32 v122, v107, v21
	v_fmac_f32_e32 v131, v106, v150
	v_fmac_f32_e32 v122, v106, v20
	v_fmac_f32_e32 v131, v104, v152
	v_fmac_f32_e32 v122, v104, v22
	v_fmac_f32_e32 v131, v105, v153
	v_fmac_f32_e32 v122, v105, v23
	v_mul_f32_e32 v125, v107, v155
	s_waitcnt lgkmcnt(2)
	v_mul_f32_e32 v123, v107, v25
	v_fmac_f32_e32 v125, v106, v154
	v_fmac_f32_e32 v123, v106, v24
	v_fmac_f32_e32 v125, v104, v156
	v_fmac_f32_e32 v17, v104, v18
	v_fmac_f32_e32 v123, v104, v26
	v_fmac_f32_e32 v125, v105, v157
	v_fmac_f32_e32 v17, v105, v19
	v_fmac_f32_e32 v123, v105, v27
	v_pk_mul_f32 v[40:41], v[158:159], v[98:99] op_sel_hi:[1,0]
	v_add_f32_e32 v124, 0, v17
	s_waitcnt lgkmcnt(0)
	v_pk_fma_f32 v[108:109], v[40:41], v[32:33], v[36:37]
	ds_read_b128 v[40:43], v60 offset:1024
	ds_read_b128 v[134:137], v60 offset:21504
	v_pk_mul_f32 v[32:33], v[160:161], v[98:99] op_sel_hi:[1,0]
	ds_read_b128 v[142:145], v60 offset:29696
	v_pk_fma_f32 v[110:111], v[32:33], v[34:35], v[38:39]
	s_waitcnt lgkmcnt(2)
	v_fma_f32 v126, v109, v41, v54
	v_cvt_pk_bf16_f32 v32, v108, v109
	v_cvt_pk_bf16_f32 v33, v110, v111
	v_fmac_f32_e32 v126, v108, v40
	global_store_dwordx2 v[86:87], v[32:33], off offset:-512
	ds_read_b128 v[32:35], v60 offset:5120
	v_fmac_f32_e32 v126, v110, v42
	v_fmac_f32_e32 v126, v111, v43
	s_waitcnt lgkmcnt(2)
	v_fma_f32 v133, v109, v135, v53
	s_waitcnt lgkmcnt(1)
	v_fma_f32 v135, v109, v143, v51
	v_fmac_f32_e32 v135, v108, v142
	v_fmac_f32_e32 v135, v110, v144
	v_fmac_f32_e32 v135, v111, v145
	ds_read_b128 v[144:147], v60 offset:50176
	s_waitcnt lgkmcnt(1)
	v_fma_f32 v127, v109, v33, v55
	v_fmac_f32_e32 v127, v108, v32
	v_fmac_f32_e32 v127, v110, v34
	v_fmac_f32_e32 v127, v111, v35
	ds_read_b128 v[36:39], v60 offset:9216
	ds_read_b128 v[32:35], v60 offset:13312
	ds_read_b128 v[40:43], v60 offset:17408
	ds_read_b128 v[138:141], v60 offset:25600
	v_fmac_f32_e32 v133, v108, v134
	v_fmac_f32_e32 v133, v110, v136
	s_waitcnt lgkmcnt(3)
	v_fma_f32 v129, v109, v37, v46
	s_waitcnt lgkmcnt(2)
	v_fma_f32 v130, v109, v33, v45
	v_fmac_f32_e32 v133, v111, v137
	v_fmac_f32_e32 v129, v108, v36
	v_fmac_f32_e32 v130, v108, v32
	s_waitcnt lgkmcnt(0)
	v_fma_f32 v134, v109, v139, v52
	v_fmac_f32_e32 v129, v110, v38
	v_fmac_f32_e32 v130, v110, v34
	v_fma_f32 v132, v109, v41, v44
	v_fmac_f32_e32 v134, v108, v138
	v_fmac_f32_e32 v129, v111, v39
	v_fmac_f32_e32 v130, v111, v35
	v_fmac_f32_e32 v132, v108, v40
	v_fmac_f32_e32 v134, v110, v140
	v_fmac_f32_e32 v132, v110, v42
	v_fmac_f32_e32 v134, v111, v141
	v_fmac_f32_e32 v132, v111, v43
	ds_read_b128 v[52:55], v60 offset:33792
	ds_read_b128 v[138:141], v60 offset:37888
	s_waitcnt lgkmcnt(1)
	v_fma_f32 v136, v109, v53, v50
	v_fmac_f32_e32 v136, v108, v52
	v_fmac_f32_e32 v136, v110, v54
	v_fmac_f32_e32 v136, v111, v55
	ds_read_b128 v[50:53], v60 offset:41984
	s_waitcnt lgkmcnt(1)
	v_fma_f32 v137, v109, v139, v49
	v_fmac_f32_e32 v137, v108, v138
	v_fmac_f32_e32 v137, v110, v140
	v_fmac_f32_e32 v137, v111, v141
	ds_read_b128 v[140:143], v60 offset:46080
	s_waitcnt lgkmcnt(1)
	v_fma_f32 v138, v109, v51, v48
	v_fmac_f32_e32 v138, v108, v50
	v_fmac_f32_e32 v138, v110, v52
	v_fmac_f32_e32 v138, v111, v53
	ds_read_b128 v[48:51], v234 offset:2048
	ds_read_b128 v[52:55], v234 offset:6144
	s_waitcnt lgkmcnt(2)
	v_fma_f32 v131, v109, v141, v131
	v_fmac_f32_e32 v131, v108, v140
	v_fmac_f32_e32 v131, v110, v142
	v_fmac_f32_e32 v131, v111, v143
	ds_read_b128 v[140:143], v60 offset:54272
	v_fma_f32 v139, v109, v145, v125
	v_fmac_f32_e32 v139, v108, v144
	v_fmac_f32_e32 v139, v110, v146
	v_fmac_f32_e32 v139, v111, v147
	ds_read_b128 v[144:147], v60 offset:58368
	s_waitcnt lgkmcnt(1)
	v_fma_f32 v148, v109, v141, v124
	v_fmac_f32_e32 v148, v108, v140
	v_fmac_f32_e32 v148, v110, v142
	v_fmac_f32_e32 v148, v111, v143
	ds_read_b128 v[140:143], v60 offset:62464
	s_waitcnt lgkmcnt(1)
	v_mul_f32_e32 v124, v109, v145
	v_fmac_f32_e32 v124, v108, v144
	v_fmac_f32_e32 v124, v110, v146
	v_fmac_f32_e32 v124, v111, v147
	v_add_f32_e32 v144, v122, v124
	s_waitcnt lgkmcnt(0)
	v_mul_f32_e32 v122, v109, v141
	v_fmac_f32_e32 v122, v108, v140
	v_fmac_f32_e32 v122, v110, v142
	v_fmac_f32_e32 v122, v111, v143
	v_add_f32_e32 v142, v123, v122
	v_mov_b32_e32 v122, v106
	v_mov_b32_e32 v123, v108
	v_mov_b32_e32 v108, v107
	v_mov_b32_e32 v106, v186
	v_mov_b32_e32 v124, v182
	v_mov_b32_e32 v140, v190
	v_mov_b32_e32 v125, v198
	v_mov_b32_e32 v107, v202
	v_pk_mul_f32 v[106:107], v[108:109], v[106:107]
	v_mov_b32_e32 v36, v187
	v_pk_fma_f32 v[106:107], v[122:123], v[124:125], v[106:107]
	v_mov_b32_e32 v124, v104
	v_mov_b32_e32 v125, v110
	v_mov_b32_e32 v110, v105
	v_mov_b32_e32 v104, v194
	v_mov_b32_e32 v141, v206
	v_pk_fma_f32 v[106:107], v[124:125], v[140:141], v[106:107]
	v_mov_b32_e32 v105, v210
	v_mov_b32_e32 v32, v183
	v_mov_b32_e32 v37, v203
	v_pk_mul_f32 v[24:25], v[108:109], v[36:37]
	v_pk_fma_f32 v[104:105], v[110:111], v[104:105], v[106:107]
	v_mov_b32_e32 v33, v199
	v_pk_fma_f32 v[24:25], v[122:123], v[32:33], v[24:25]
	v_mov_b32_e32 v40, v191
	v_add_f32_e32 v16, 0, v104
	v_mov_b32_e32 v41, v207
	v_pk_fma_f32 v[20:21], v[124:125], v[40:41], v[24:25]
	v_mov_b32_e32 v44, v195
	v_add_f32_e32 v107, v16, v105
	v_mov_b32_e32 v45, v211
	v_pk_fma_f32 v[16:17], v[110:111], v[44:45], v[20:21]
	v_mov_b32_e32 v20, v188
	v_add_f32_e32 v16, 0, v16
	v_mov_b32_e32 v21, v204
	v_add_f32_e32 v105, v16, v17
	v_mov_b32_e32 v16, v184
	v_mov_b32_e32 v17, v200
	v_pk_mul_f32 v[20:21], v[108:109], v[20:21]
	v_mov_b32_e32 v38, v189
	v_pk_fma_f32 v[16:17], v[122:123], v[16:17], v[20:21]
	v_mov_b32_e32 v20, v192
	v_mov_b32_e32 v21, v208
	v_pk_fma_f32 v[16:17], v[124:125], v[20:21], v[16:17]
	v_mov_b32_e32 v20, v196
	v_mov_b32_e32 v21, v212
	v_pk_fma_f32 v[16:17], v[110:111], v[20:21], v[16:17]
	v_mov_b32_e32 v34, v185
	v_add_f32_e32 v16, 0, v16
	v_add_f32_e32 v106, v16, v17
	v_mov_b32_e32 v39, v205
	v_pk_mul_f32 v[16:17], v[108:109], v[38:39]
	v_mov_b32_e32 v42, v193
	v_mov_b32_e32 v35, v201
	v_pk_fma_f32 v[16:17], v[122:123], v[34:35], v[16:17]
	v_mov_b32_e32 v46, v197
	v_mov_b32_e32 v43, v209
	v_pk_fma_f32 v[16:17], v[124:125], v[42:43], v[16:17]
	v_pk_mul_f32 v[20:21], v[102:103], v[98:99] op_sel_hi:[1,0]
	v_mov_b32_e32 v47, v213
	v_pk_fma_f32 v[16:17], v[110:111], v[46:47], v[16:17]
	v_pk_fma_f32 v[50:51], v[20:21], v[50:51], v[54:55]
	v_add_f32_e32 v16, 0, v16
	v_add_f32_e32 v104, v16, v17
	v_pk_mul_f32 v[16:17], v[100:101], v[98:99] op_sel_hi:[1,0]
	v_cvt_pk_bf16_f32 v21, v50, v51
	v_pk_fma_f32 v[48:49], v[16:17], v[48:49], v[52:53]
	ds_read_b128 v[16:19], v60 offset:2048
	v_cvt_pk_bf16_f32 v20, v48, v49
	global_store_dwordx2 v[86:87], v[20:21], off
	ds_read_b128 v[20:23], v60 offset:6144
	v_pk_mul_f32 v[46:47], v[94:95], v[98:99] op_sel_hi:[1,0]
	s_waitcnt lgkmcnt(1)
	v_fma_f32 v42, v49, v17, v126
	v_fmac_f32_e32 v42, v48, v16
	v_fmac_f32_e32 v42, v50, v18
	v_fmac_f32_e32 v42, v51, v19
	ds_read_b128 v[16:19], v60 offset:10240
	s_waitcnt lgkmcnt(1)
	v_fma_f32 v41, v49, v21, v127
	v_fmac_f32_e32 v41, v48, v20
	v_fmac_f32_e32 v41, v50, v22
	v_fmac_f32_e32 v41, v51, v23
	ds_read_b128 v[20:23], v60 offset:14336
	s_waitcnt lgkmcnt(1)
	v_fma_f32 v40, v49, v17, v129
	v_fmac_f32_e32 v40, v48, v16
	v_fmac_f32_e32 v40, v50, v18
	v_fmac_f32_e32 v40, v51, v19
	ds_read_b128 v[16:19], v60 offset:18432
	ds_read_b128 v[32:35], v234 offset:3072
	ds_read_b128 v[36:39], v234 offset:7168
	s_waitcnt lgkmcnt(3)
	v_fma_f32 v45, v49, v21, v130
	v_fmac_f32_e32 v45, v48, v20
	v_fmac_f32_e32 v45, v50, v22
	v_fmac_f32_e32 v45, v51, v23
	ds_read_b128 v[20:23], v60 offset:22528
	s_waitcnt lgkmcnt(3)
	v_fma_f32 v44, v49, v17, v132
	v_fmac_f32_e32 v44, v48, v16
	v_fmac_f32_e32 v44, v50, v18
	v_fmac_f32_e32 v44, v51, v19
	ds_read_b128 v[16:19], v60 offset:26624
	s_waitcnt lgkmcnt(1)
	v_fma_f32 v124, v49, v21, v133
	v_fmac_f32_e32 v124, v48, v20
	v_fmac_f32_e32 v124, v50, v22
	v_fmac_f32_e32 v124, v51, v23
	ds_read_b128 v[20:23], v60 offset:30720
	s_waitcnt lgkmcnt(1)
	v_fma_f32 v123, v49, v17, v134
	v_fmac_f32_e32 v123, v48, v16
	v_fmac_f32_e32 v123, v50, v18
	v_fmac_f32_e32 v123, v51, v19
	s_waitcnt lgkmcnt(0)
	v_fma_f32 v122, v49, v21, v135
	v_fmac_f32_e32 v122, v48, v20
	v_fmac_f32_e32 v122, v50, v22
	ds_read_b128 v[16:19], v60 offset:34816
	v_fmac_f32_e32 v122, v51, v23
	ds_read_b128 v[20:23], v60 offset:38912
	s_waitcnt lgkmcnt(1)
	v_fma_f32 v111, v49, v17, v136
	v_fmac_f32_e32 v111, v48, v16
	v_fmac_f32_e32 v111, v50, v18
	s_waitcnt lgkmcnt(0)
	v_fma_f32 v110, v49, v21, v137
	v_fmac_f32_e32 v110, v48, v20
	v_fmac_f32_e32 v111, v51, v19
	v_fmac_f32_e32 v110, v50, v22
	ds_read_b128 v[16:19], v60 offset:43008
	v_fmac_f32_e32 v110, v51, v23
	ds_read_b128 v[20:23], v60 offset:47104
	s_waitcnt lgkmcnt(1)
	v_fma_f32 v109, v49, v17, v138
	v_fmac_f32_e32 v109, v48, v16
	v_fmac_f32_e32 v109, v50, v18
	s_waitcnt lgkmcnt(0)
	v_fma_f32 v108, v49, v21, v131
	v_fmac_f32_e32 v108, v48, v20
	v_fmac_f32_e32 v109, v51, v19
	v_fmac_f32_e32 v108, v50, v22
	ds_read_b128 v[16:19], v60 offset:51200
	v_fmac_f32_e32 v108, v51, v23
	ds_read_b128 v[20:23], v60 offset:55296
	s_waitcnt lgkmcnt(1)
	v_fma_f32 v103, v49, v17, v139
	v_fmac_f32_e32 v103, v48, v16
	v_fmac_f32_e32 v103, v50, v18
	s_waitcnt lgkmcnt(0)
	v_fma_f32 v102, v49, v21, v148
	v_fmac_f32_e32 v102, v48, v20
	v_fmac_f32_e32 v103, v51, v19
	v_fmac_f32_e32 v102, v50, v22
	ds_read_b128 v[16:19], v60 offset:59392
	v_fmac_f32_e32 v102, v51, v23
	ds_read_b128 v[20:23], v60 offset:63488
	s_waitcnt lgkmcnt(1)
	v_fma_f32 v100, v49, v17, v144
	v_fmac_f32_e32 v100, v48, v16
	v_fmac_f32_e32 v100, v50, v18
	s_waitcnt lgkmcnt(0)
	v_fma_f32 v101, v49, v21, v142
	v_fmac_f32_e32 v101, v48, v20
	v_fmac_f32_e32 v101, v50, v22
	v_fmac_f32_e32 v100, v51, v19
	v_fmac_f32_e32 v101, v51, v23
	v_pk_fma_f32 v[52:53], v[46:47], v[32:33], v[36:37]
	v_pk_mul_f32 v[32:33], v[96:97], v[98:99] op_sel_hi:[1,0]
	ds_read_b128 v[94:97], v60 offset:3072
	v_pk_fma_f32 v[54:55], v[32:33], v[34:35], v[38:39]
	v_cvt_pk_bf16_f32 v32, v52, v53
	v_cvt_pk_bf16_f32 v33, v54, v55
	global_store_dwordx2 v[86:87], v[32:33], off offset:512
	ds_read_b128 v[32:35], v60 offset:7168
	s_waitcnt lgkmcnt(1)
	v_mul_f32_e32 v36, v53, v95
	v_fmac_f32_e32 v36, v52, v94
	v_fmac_f32_e32 v36, v54, v96
	v_fmac_f32_e32 v36, v55, v97
	v_add_f32_e32 v94, v42, v36
	ds_read_b128 v[36:39], v60 offset:11264
	ds_read_b128 v[130:133], v60 offset:15360
	s_waitcnt lgkmcnt(2)
	v_fma_f32 v95, v53, v33, v41
	v_fmac_f32_e32 v95, v52, v32
	v_fmac_f32_e32 v95, v54, v34
	s_waitcnt lgkmcnt(1)
	v_fma_f32 v96, v53, v37, v40
	v_fmac_f32_e32 v96, v52, v36
	v_fmac_f32_e32 v96, v54, v38
	v_fmac_f32_e32 v95, v55, v35
	v_fmac_f32_e32 v96, v55, v39
	ds_read_b128 v[40:43], v60 offset:19456
	s_waitcnt lgkmcnt(1)
	v_fma_f32 v97, v53, v131, v45
	v_fmac_f32_e32 v97, v52, v130
	v_fmac_f32_e32 v97, v54, v132
	v_fmac_f32_e32 v97, v55, v133
	ds_read_b128 v[130:133], v60 offset:23552
	s_waitcnt lgkmcnt(1)
	v_fma_f32 v125, v53, v41, v44
	v_fmac_f32_e32 v125, v52, v40
	v_fmac_f32_e32 v125, v54, v42
	v_fmac_f32_e32 v125, v55, v43
	ds_read_b128 v[134:137], v60 offset:27648
	s_waitcnt lgkmcnt(1)
	v_fma_f32 v124, v53, v131, v124
	v_fmac_f32_e32 v124, v52, v130
	v_fmac_f32_e32 v124, v54, v132
	v_fmac_f32_e32 v124, v55, v133
	ds_read_b128 v[130:133], v60 offset:31744
	s_waitcnt lgkmcnt(1)
	v_fma_f32 v98, v53, v135, v123
	v_fmac_f32_e32 v98, v52, v134
	v_fmac_f32_e32 v98, v54, v136
	v_fmac_f32_e32 v98, v55, v137
	ds_read_b128 v[134:137], v60 offset:35840
	s_waitcnt lgkmcnt(1)
	v_fma_f32 v122, v53, v131, v122
	v_fmac_f32_e32 v122, v52, v130
	v_fmac_f32_e32 v122, v54, v132
	v_fmac_f32_e32 v122, v55, v133
	ds_read_b128 v[130:133], v60 offset:39936
	s_waitcnt lgkmcnt(1)
	v_fma_f32 v111, v53, v135, v111
	v_fmac_f32_e32 v111, v52, v134
	v_fmac_f32_e32 v111, v54, v136
	v_fmac_f32_e32 v111, v55, v137
	ds_read_b128 v[134:137], v60 offset:44032
	s_waitcnt lgkmcnt(1)
	v_fma_f32 v110, v53, v131, v110
	v_fmac_f32_e32 v110, v52, v130
	v_fmac_f32_e32 v110, v54, v132
	v_fmac_f32_e32 v110, v55, v133
	ds_read_b128 v[130:133], v60 offset:48128
	s_waitcnt lgkmcnt(1)
	v_fma_f32 v109, v53, v135, v109
	v_fmac_f32_e32 v109, v52, v134
	v_fmac_f32_e32 v109, v54, v136
	v_fmac_f32_e32 v109, v55, v137
	ds_read_b128 v[134:137], v60 offset:52224
	s_waitcnt lgkmcnt(1)
	v_fma_f32 v108, v53, v131, v108
	v_fmac_f32_e32 v108, v52, v130
	v_fmac_f32_e32 v108, v54, v132
	v_fmac_f32_e32 v108, v55, v133
	ds_read_b128 v[130:133], v60 offset:56320
	s_waitcnt lgkmcnt(1)
	v_fma_f32 v103, v53, v135, v103
	v_fmac_f32_e32 v103, v52, v134
	v_fmac_f32_e32 v103, v54, v136
	v_fmac_f32_e32 v103, v55, v137
	ds_read_b128 v[134:137], v60 offset:60416
	s_waitcnt lgkmcnt(1)
	v_fma_f32 v102, v53, v131, v102
	v_fmac_f32_e32 v102, v52, v130
	v_fmac_f32_e32 v102, v54, v132
	v_fmac_f32_e32 v102, v55, v133
	ds_read_b128 v[130:133], v60 offset:64512
	s_waitcnt lgkmcnt(1)
	v_fma_f32 v123, v53, v135, v100
	v_fmac_f32_e32 v123, v52, v134
	v_fmac_f32_e32 v123, v54, v136
	v_fmac_f32_e32 v123, v55, v137
	s_waitcnt lgkmcnt(0)
	v_fma_f32 v129, v53, v131, v101
	v_fmac_f32_e32 v129, v52, v130
	v_fmac_f32_e32 v129, v54, v132
	v_fmac_f32_e32 v129, v55, v133
	v_mov_b32_e32 v100, v48
	v_mov_b32_e32 v101, v52
	v_mov_b32_e32 v52, v49
	v_mov_b32_e32 v48, v218
	v_mov_b32_e32 v126, v214
	v_mov_b32_e32 v130, v222
	v_mov_b32_e32 v127, v230
	v_mov_b32_e32 v49, v238
	v_pk_mul_f32 v[48:49], v[52:53], v[48:49]
	v_mov_b32_e32 v36, v219
	v_pk_fma_f32 v[48:49], v[100:101], v[126:127], v[48:49]
	v_mov_b32_e32 v126, v50
	v_mov_b32_e32 v127, v54
	v_mov_b32_e32 v131, v242
	v_pk_fma_f32 v[48:49], v[126:127], v[130:131], v[48:49]
	v_mov_b32_e32 v54, v51
	v_mov_b32_e32 v50, v226
	v_mov_b32_e32 v51, v246
	v_mov_b32_e32 v32, v215
	v_mov_b32_e32 v37, v239
	v_pk_mul_f32 v[24:25], v[52:53], v[36:37]
	v_pk_fma_f32 v[48:49], v[54:55], v[50:51], v[48:49]
	v_mov_b32_e32 v33, v231
	v_pk_fma_f32 v[24:25], v[100:101], v[32:33], v[24:25]
	v_mov_b32_e32 v40, v223
	v_add_f32_e32 v16, v107, v48
	v_mov_b32_e32 v41, v243
	v_pk_fma_f32 v[20:21], v[126:127], v[40:41], v[24:25]
	v_mov_b32_e32 v44, v227
	v_add_f32_e32 v28, v16, v49
	v_mov_b32_e32 v45, v247
	v_pk_fma_f32 v[16:17], v[54:55], v[44:45], v[20:21]
	v_mov_b32_e32 v20, v220
	v_add_f32_e32 v16, v105, v16
	v_mov_b32_e32 v21, v240
	v_add_f32_e32 v24, v16, v17
	v_mov_b32_e32 v16, v216
	v_mov_b32_e32 v17, v232
	v_pk_mul_f32 v[20:21], v[52:53], v[20:21]
	v_mov_b32_e32 v38, v221
	v_pk_fma_f32 v[16:17], v[100:101], v[16:17], v[20:21]
	v_mov_b32_e32 v20, v224
	v_mov_b32_e32 v21, v244
	v_pk_fma_f32 v[16:17], v[126:127], v[20:21], v[16:17]
	v_mov_b32_e32 v20, v228
	v_mov_b32_e32 v21, v248
	v_pk_fma_f32 v[16:17], v[54:55], v[20:21], v[16:17]
	v_mov_b32_e32 v34, v217
	v_add_f32_e32 v16, v106, v16
	v_add_f32_e32 v20, v16, v17
	v_mov_b32_e32 v39, v241
	v_pk_mul_f32 v[16:17], v[52:53], v[38:39]
	v_mov_b32_e32 v42, v225
	v_mov_b32_e32 v35, v233
	v_pk_fma_f32 v[16:17], v[100:101], v[34:35], v[16:17]
	v_mov_b32_e32 v46, v229
	v_mov_b32_e32 v43, v245
	v_pk_fma_f32 v[16:17], v[126:127], v[42:43], v[16:17]
	v_mov_b32_e32 v47, v249
	v_pk_fma_f32 v[16:17], v[54:55], v[46:47], v[16:17]
	v_add_f32_e32 v16, v104, v16
	v_add_f32_e32 v22, v16, v17
	v_add_f32_dpp v250, v24, v24 row_mirror row_mask:0xf bank_mask:0xf bound_ctrl:1
	v_add_f32_dpp v250, v20, v20 row_mirror row_mask:0xf bank_mask:0xc bound_ctrl:1
	v_add_f32_dpp v251, v28, v28 row_mirror row_mask:0xf bank_mask:0xf bound_ctrl:1
	v_add_f32_dpp v251, v22, v22 row_mirror row_mask:0xf bank_mask:0xc bound_ctrl:1
	v_add_f32_dpp v250, v250, v250 row_half_mirror row_mask:0xf bank_mask:0xf bound_ctrl:1
	s_nop 0
	v_add_f32_dpp v250, v251, v251 row_half_mirror row_mask:0xf bank_mask:0xa bound_ctrl:1
	s_nop 1
	v_add_f32_dpp v250, v250, v250 quad_perm:[1,0,3,2] row_mask:0xf bank_mask:0xf bound_ctrl:1
	s_nop 1
	v_add_f32_dpp v250, v250, v250 quad_perm:[2,3,0,1] row_mask:0xf bank_mask:0xf bound_ctrl:1
	s_nop 0
	v_readlane_b32 s2, v250, 20
	v_readlane_b32 s4, v250, 52
	v_readlane_b32 s0, v250, 4
	v_readlane_b32 s1, v250, 36
	v_mov_b32_e32 v16, s2
	v_mov_b32_e32 v17, s4
	v_readlane_b32 s2, v250, 16
	v_readlane_b32 s4, v250, 48
	v_pk_add_f32 v[16:17], s[0:1], v[16:17]
	v_readlane_b32 s0, v250, 0
	v_readlane_b32 s1, v250, 32
	v_mov_b32_e32 v18, s2
	v_mov_b32_e32 v19, s4
	v_readlane_b32 s2, v250, 24
	v_readlane_b32 s4, v250, 56
	v_pk_add_f32 v[18:19], s[0:1], v[18:19]
	v_readlane_b32 s0, v250, 8
	v_readlane_b32 s1, v250, 40
	v_mov_b32_e32 v20, s2
	v_mov_b32_e32 v21, s4
	v_pk_add_f32 v[20:21], s[0:1], v[20:21]
	v_mov_b32_e32 v25, v18
	v_add_f32_e32 v26, v20, v21
	v_mov_b32_e32 v18, v17
	v_readlane_b32 s2, v250, 28
	v_readlane_b32 s4, v250, 60
	v_readlane_b32 s0, v250, 12
	v_readlane_b32 s1, v250, 44
	v_mov_b32_e32 v20, s2
	v_mov_b32_e32 v21, s4
	v_pk_add_f32 v[20:21], s[0:1], v[20:21]
	v_add_f32_e32 v27, v20, v21
	v_mov_b32_e32 v24, v16
	v_pk_add_f32 v[16:17], v[24:25], v[18:19]
	v_mov_b32_e32 v20, v178
	v_mov_b32_e32 v21, v179
	v_mov_b32_e32 v22, v180
	v_mov_b32_e32 v23, v181
	v_add_f32_e32 v19, v26, v22
	v_pk_add_f32 v[16:17], v[16:17], v[20:21]
	v_add_f32_e32 v18, v27, v23
	v_cmp_gt_f32_e32 vcc, v17, v16
	v_mov_b32_e32 v22, 0
	s_nop 0
	v_cndmask_b32_e32 v20, v16, v17, vcc
	v_cmp_gt_f32_e64 s[18:19], v19, v20
	v_cndmask_b32_e64 v21, 0, 1, vcc
	s_and_b64 s[14:15], s[18:19], exec
	v_cndmask_b32_e64 v20, v20, v19, s[18:19]
	v_cmp_ngt_f32_e64 s[0:1], v18, v20
	v_readfirstlane_b32 s2, v21
	s_cselect_b32 s2, 2, s2
	s_and_b64 s[14:15], s[0:1], exec
	s_cselect_b32 s2, s2, 3
	s_cmp_eq_u32 s2, 0
	s_cbranch_scc0 .Lmy_rsela_1
	v_add_f32_dpp v94, v94, v94 row_mirror row_mask:0xf bank_mask:0xf bound_ctrl:1
	v_add_f32_dpp v94, v95, v95 row_mirror row_mask:0xf bank_mask:0xc bound_ctrl:1
	v_add_f32_dpp v96, v96, v96 row_mirror row_mask:0xf bank_mask:0xf bound_ctrl:1
	v_add_f32_dpp v96, v97, v97 row_mirror row_mask:0xf bank_mask:0xc bound_ctrl:1
	v_add_f32_dpp v94, v94, v94 row_half_mirror row_mask:0xf bank_mask:0xf bound_ctrl:1
	s_nop 0
	v_add_f32_dpp v94, v96, v96 row_half_mirror row_mask:0xf bank_mask:0xa bound_ctrl:1
	s_nop 1
	v_add_f32_dpp v94, v94, v94 quad_perm:[1,0,3,2] row_mask:0xf bank_mask:0xf bound_ctrl:1
	s_nop 1
	v_add_f32_dpp v94, v94, v94 quad_perm:[2,3,0,1] row_mask:0xf bank_mask:0xf bound_ctrl:1
	s_nop 0
	v_readlane_b32 s20, v94, 0
	v_readlane_b32 s4, v94, 16
	v_readlane_b32 s21, v94, 32
	v_readlane_b32 s5, v94, 48
	v_readlane_b32 s91, v94, 8
	v_readlane_b32 s95, v94, 24
	v_readlane_b32 s94, v94, 40
	v_readlane_b32 s92, v94, 56
	v_readlane_b32 s6, v94, 4
	v_readlane_b32 s75, v94, 20
	v_readlane_b32 s74, v94, 36
	v_readlane_b32 s84, v94, 52
	v_readlane_b32 s97, v94, 12
	v_readlane_b32 s9, v94, 28
	v_readlane_b32 s8, v94, 44
	v_readlane_b32 s12, v94, 60
	s_branch .Lmy_rsela_end
.Lmy_rsela_1:
	s_cmp_eq_u32 s2, 1
	s_cbranch_scc0 .Lmy_rsela_2
	v_add_f32_dpp v125, v125, v125 row_mirror row_mask:0xf bank_mask:0xf bound_ctrl:1
	v_add_f32_dpp v125, v124, v124 row_mirror row_mask:0xf bank_mask:0xc bound_ctrl:1
	v_add_f32_dpp v98, v98, v98 row_mirror row_mask:0xf bank_mask:0xf bound_ctrl:1
	v_add_f32_dpp v98, v122, v122 row_mirror row_mask:0xf bank_mask:0xc bound_ctrl:1
	v_add_f32_dpp v125, v125, v125 row_half_mirror row_mask:0xf bank_mask:0xf bound_ctrl:1
	s_nop 0
	v_add_f32_dpp v125, v98, v98 row_half_mirror row_mask:0xf bank_mask:0xa bound_ctrl:1
	s_nop 1
	v_add_f32_dpp v125, v125, v125 quad_perm:[1,0,3,2] row_mask:0xf bank_mask:0xf bound_ctrl:1
	s_nop 1
	v_add_f32_dpp v125, v125, v125 quad_perm:[2,3,0,1] row_mask:0xf bank_mask:0xf bound_ctrl:1
	s_nop 0
	v_readlane_b32 s59, v125, 0
	v_readlane_b32 s61, v125, 16
	v_readlane_b32 s60, v125, 32
	v_readlane_b32 s82, v125, 48
	v_readlane_b32 s52, v125, 8
	v_readlane_b32 s54, v125, 24
	v_readlane_b32 s53, v125, 40
	v_readlane_b32 s93, v125, 56
	v_readlane_b32 s85, v125, 4
	v_readlane_b32 s87, v125, 20
	v_readlane_b32 s86, v125, 36
	v_readlane_b32 s90, v125, 52
	v_readlane_b32 s13, v125, 12
	v_readlane_b32 s24, v125, 28
	v_readlane_b32 s16, v125, 44
	v_readlane_b32 s17, v125, 60
	s_branch .Lmy_rsela_end
.Lmy_rsela_2:
	s_cmp_eq_u32 s2, 2
	s_cbranch_scc0 .Lmy_rsela_3
	v_add_f32_dpp v111, v111, v111 row_mirror row_mask:0xf bank_mask:0xf bound_ctrl:1
	v_add_f32_dpp v111, v110, v110 row_mirror row_mask:0xf bank_mask:0xc bound_ctrl:1
	v_add_f32_dpp v109, v109, v109 row_mirror row_mask:0xf bank_mask:0xf bound_ctrl:1
	v_add_f32_dpp v109, v108, v108 row_mirror row_mask:0xf bank_mask:0xc bound_ctrl:1
	v_add_f32_dpp v111, v111, v111 row_half_mirror row_mask:0xf bank_mask:0xf bound_ctrl:1
	s_nop 0
	v_add_f32_dpp v111, v109, v109 row_half_mirror row_mask:0xf bank_mask:0xa bound_ctrl:1
	s_nop 1
	v_add_f32_dpp v111, v111, v111 quad_perm:[1,0,3,2] row_mask:0xf bank_mask:0xf bound_ctrl:1
	s_nop 1
	v_add_f32_dpp v111, v111, v111 quad_perm:[2,3,0,1] row_mask:0xf bank_mask:0xf bound_ctrl:1
	s_nop 0
	v_readlane_b32 s83, v111, 0
	v_readlane_b32 s89, v111, 16
	v_readlane_b32 s88, v111, 32
	v_readlane_b32 s96, v111, 48
	v_readlane_b32 s55, v111, 8
	v_readlane_b32 s57, v111, 24
	v_readlane_b32 s56, v111, 40
	v_readlane_b32 s58, v111, 56
	v_readlane_b32 s46, v111, 4
	v_readlane_b32 s48, v111, 20
	v_readlane_b32 s47, v111, 36
	v_readlane_b32 s49, v111, 52
	v_readlane_b32 s38, v111, 12
	v_readlane_b32 s40, v111, 28
	v_readlane_b32 s39, v111, 44
	v_readlane_b32 s41, v111, 60
	s_branch .Lmy_rsela_end
.Lmy_rsela_3:
	v_add_f32_dpp v103, v103, v103 row_mirror row_mask:0xf bank_mask:0xf bound_ctrl:1
	v_add_f32_dpp v103, v102, v102 row_mirror row_mask:0xf bank_mask:0xc bound_ctrl:1
	v_add_f32_dpp v123, v123, v123 row_mirror row_mask:0xf bank_mask:0xf bound_ctrl:1
	v_add_f32_dpp v123, v129, v129 row_mirror row_mask:0xf bank_mask:0xc bound_ctrl:1
	v_add_f32_dpp v103, v103, v103 row_half_mirror row_mask:0xf bank_mask:0xf bound_ctrl:1
	s_nop 0
	v_add_f32_dpp v103, v123, v123 row_half_mirror row_mask:0xf bank_mask:0xa bound_ctrl:1
	s_nop 1
	v_add_f32_dpp v103, v103, v103 quad_perm:[1,0,3,2] row_mask:0xf bank_mask:0xf bound_ctrl:1
	s_nop 1
	v_add_f32_dpp v103, v103, v103 quad_perm:[2,3,0,1] row_mask:0xf bank_mask:0xf bound_ctrl:1
	s_nop 0
	v_readlane_b32 s34, v103, 0
	v_readlane_b32 s36, v103, 16
	v_readlane_b32 s35, v103, 32
	v_readlane_b32 s37, v103, 48
	v_readlane_b32 s29, v103, 8
	v_readlane_b32 s31, v103, 24
	v_readlane_b32 s30, v103, 40
	v_readlane_b32 s33, v103, 56
	v_readlane_b32 s25, v103, 4
	v_readlane_b32 s28, v103, 20
	v_readlane_b32 s50, v103, 36
	v_readlane_b32 s51, v103, 52
	v_readlane_b32 s42, v103, 12
	v_readlane_b32 s44, v103, 28
	v_readlane_b32 s43, v103, 44
	v_readlane_b32 s45, v103, 60
.Lmy_rsela_end:
	s_cmp_eq_u32 s2, 0
	s_cselect_b64 s[26:27], -1, 0
	s_cmp_lg_u32 s2, 0
	v_mov_b32_e32 v21, 0
	v_cmp_gt_f32_e64 s[14:15], v18, v20
	s_waitcnt lgkmcnt(0)
	s_cbranch_scc0 .LBB0_560
	v_cndmask_b32_e64 v23, 0, 1, s[26:27]
	v_cmp_ne_u32_e64 s[20:21], 1, v23
	s_andn2_b64 vcc, exec, s[26:27]
	s_cbranch_vccz .LBB0_561

.LBB0_1676:
	s_add_i32 s21, s19, 1
	s_waitcnt vmcnt(0)
	v_mov_b64_e32 v[38:39], v[84:85]
	v_mov_b64_e32 v[32:33], v[92:93]
	v_mov_b64_e32 v[34:35], v[90:91]
	v_mov_b64_e32 v[36:37], v[88:89]
	v_mov_b32_e32 v0, s21
	v_min_u32_e32 v0, 15, v0
	v_mov_b32_e32 v1, 0
	v_lshl_add_u64 v[0:1], v[82:83], 0, v[0:1]
	v_lshlrev_b64 v[2:3], 12, v[0:1]
	v_lshlrev_b64 v[0:1], 11, v[0:1]
	v_lshl_add_u64 v[12:13], v[62:63], 0, v[2:3]
	v_lshl_add_u64 v[92:93], v[64:65], 0, v[0:1]
	global_load_dwordx4 v[0:3], v[12:13], off nt
	global_load_dwordx2 v[84:85], v[92:93], off nt
	global_load_dwordx4 v[4:7], v[12:13], off offset:1024 nt
	global_load_dwordx2 v[88:89], v[92:93], off offset:512 nt
	global_load_dwordx4 v[8:11], v[12:13], off offset:2048 nt
	global_load_dwordx2 v[90:91], v[92:93], off offset:1024 nt
	s_nop 0
	global_load_dwordx4 v[12:15], v[12:13], off offset:3072 nt
	s_nop 0
	global_load_dwordx2 v[92:93], v[92:93], off offset:1536 nt
	v_lshlrev_b32_e32 v40, 16, v38
	v_and_b32_e32 v41, 0xffff0000, v38
	v_lshlrev_b32_e32 v38, 16, v39
	v_and_b32_e32 v39, 0xffff0000, v39
	v_lshlrev_b32_e32 v54, 16, v36
	v_and_b32_e32 v55, 0xffff0000, v36
	v_lshlrev_b32_e32 v94, 16, v37
	v_and_b32_e32 v95, 0xffff0000, v37
	v_lshlrev_b32_e32 v96, 16, v34
	v_and_b32_e32 v97, 0xffff0000, v34
	v_lshlrev_b32_e32 v100, 16, v35
	v_and_b32_e32 v101, 0xffff0000, v35
	v_lshlrev_b32_e32 v102, 16, v32
	v_and_b32_e32 v103, 0xffff0000, v32
	v_lshlrev_b32_e32 v104, 16, v33
	v_and_b32_e32 v105, 0xffff0000, v33
	v_pk_fma_f32 v[106:107], v[30:31], s[20:21], v[38:39] op_sel_hi:[1,0,1]
	ds_read_b128 v[30:33], v234
	ds_read_b128 v[34:37], v234 offset:4096
	v_pk_fma_f32 v[28:29], v[28:29], s[20:21], v[40:41] op_sel_hi:[1,0,1]
	v_pk_fma_f32 v[20:21], v[20:21], s[20:21], v[54:55] op_sel_hi:[1,0,1]
	v_add_f32_e32 v38, v28, v29
	v_add_f32_e32 v38, v38, v106
	v_pk_fma_f32 v[22:23], v[22:23], s[20:21], v[94:95] op_sel_hi:[1,0,1]
	v_add_f32_e32 v54, v20, v21
	v_pk_fma_f32 v[24:25], v[24:25], s[20:21], v[96:97] op_sel_hi:[1,0,1]
	v_add_f32_e32 v38, v107, v38
	v_add_f32_e32 v54, v54, v22
	v_pk_fma_f32 v[26:27], v[26:27], s[20:21], v[100:101] op_sel_hi:[1,0,1]
	v_add_f32_e32 v55, v24, v25
	v_add_f32_e32 v98, 0, v38
	v_add_f32_e32 v54, v23, v54
	v_add_f32_e32 v55, v55, v26
	v_add_f32_e32 v54, v98, v54
	v_add_f32_e32 v55, v27, v55
	v_pk_fma_f32 v[16:17], v[16:17], s[20:21], v[102:103] op_sel_hi:[1,0,1]
	v_add_f32_e32 v54, v54, v55
	v_pk_fma_f32 v[18:19], v[18:19], s[20:21], v[104:105] op_sel_hi:[1,0,1]
	v_add_f32_e32 v55, v16, v17
	v_add_f32_e32 v55, v55, v18
	v_add_f32_e32 v55, v19, v55
	v_add_f32_e32 v54, v54, v55
	ds_read_b128 v[38:41], v60
	ds_read_b128 v[42:45], v60 offset:4096
	ds_read_b128 v[46:49], v60 offset:8192
	ds_read_b128 v[50:53], v60 offset:12288
	ds_read_b128 v[108:111], v60 offset:16384
	ds_read_b128 v[122:125], v60 offset:20480
	ds_read_b128 v[130:133], v60 offset:24576
	ds_read_b128 v[134:137], v60 offset:28672
	ds_read_b128 v[138:141], v60 offset:32768
	ds_read_b128 v[142:145], v60 offset:36864
	ds_read_b128 v[146:149], v60 offset:40960
	ds_read_b128 v[150:153], v60 offset:45056
	ds_read_b128 v[154:157], v60 offset:49152
	v_add_f32_dpp v54, v54, v54 quad_perm:[1,0,3,2] row_mask:0xf bank_mask:0xf bound_ctrl:1
	s_nop 1
	v_add_f32_dpp v54, v54, v54 quad_perm:[2,3,0,1] row_mask:0xf bank_mask:0xf bound_ctrl:1
	s_nop 1
	v_add_f32_dpp v54, v54, v54 row_half_mirror row_mask:0xf bank_mask:0xf bound_ctrl:1
	s_nop 1
	v_add_f32_dpp v54, v54, v54 row_mirror row_mask:0xf bank_mask:0xf bound_ctrl:1
	s_nop 0
	v_readlane_b32 s2, v54, 16
	v_readlane_b32 s10, v54, 48
	v_readlane_b32 s0, v54, 0
	v_readlane_b32 s1, v54, 32
	v_mov_b32_e32 v54, s2
	v_mov_b32_e32 v55, s10
	v_pk_add_f32 v[54:55], s[0:1], v[54:55]
	s_nop 0
	v_add_f32_e32 v54, v54, v55
	v_mul_f32_e32 v54, 0x3a800000, v54
	v_pk_add_f32 v[28:29], v[28:29], v[54:55] op_sel_hi:[1,0] neg_lo:[0,1] neg_hi:[0,1]
	v_pk_add_f32 v[126:127], v[106:107], v[54:55] op_sel_hi:[1,0] neg_lo:[0,1] neg_hi:[0,1]
	v_pk_mul_f32 v[104:105], v[28:29], v[28:29]
	v_pk_mul_f32 v[106:107], v[126:127], v[126:127]
	v_pk_add_f32 v[158:159], v[20:21], v[54:55] op_sel_hi:[1,0] neg_lo:[0,1] neg_hi:[0,1]
	v_pk_add_f32 v[160:161], v[22:23], v[54:55] op_sel_hi:[1,0] neg_lo:[0,1] neg_hi:[0,1]
	v_pk_add_f32 v[100:101], v[24:25], v[54:55] op_sel_hi:[1,0] neg_lo:[0,1] neg_hi:[0,1]
	v_pk_add_f32 v[102:103], v[26:27], v[54:55] op_sel_hi:[1,0] neg_lo:[0,1] neg_hi:[0,1]
	v_pk_add_f32 v[94:95], v[16:17], v[54:55] op_sel_hi:[1,0] neg_lo:[0,1] neg_hi:[0,1]
	v_pk_add_f32 v[96:97], v[18:19], v[54:55] op_sel_hi:[1,0] neg_lo:[0,1] neg_hi:[0,1]
	v_add_f32_e32 v54, v104, v105
	v_add_f32_e32 v54, v106, v54
	v_pk_mul_f32 v[20:21], v[158:159], v[158:159]
	v_add_f32_e32 v54, v107, v54
	v_add_f32_e32 v20, v20, v54
	v_pk_mul_f32 v[22:23], v[160:161], v[160:161]
	v_add_f32_e32 v20, v21, v20
	v_add_f32_e32 v20, v22, v20
	v_pk_mul_f32 v[24:25], v[100:101], v[100:101]
	v_add_f32_e32 v20, v23, v20
	v_add_f32_e32 v20, v24, v20
	v_pk_mul_f32 v[26:27], v[102:103], v[102:103]
	v_add_f32_e32 v20, v25, v20
	v_add_f32_e32 v20, v26, v20
	v_pk_mul_f32 v[16:17], v[94:95], v[94:95]
	v_add_f32_e32 v20, v27, v20
	v_add_f32_e32 v16, v16, v20
	v_pk_mul_f32 v[18:19], v[96:97], v[96:97]
	v_add_f32_e32 v16, v17, v16
	v_add_f32_e32 v16, v18, v16
	v_add_f32_e32 v16, v19, v16
	s_nop 1
	v_add_f32_dpp v16, v16, v16 quad_perm:[1,0,3,2] row_mask:0xf bank_mask:0xf bound_ctrl:1
	s_nop 1
	v_add_f32_dpp v16, v16, v16 quad_perm:[2,3,0,1] row_mask:0xf bank_mask:0xf bound_ctrl:1
	s_nop 1
	v_add_f32_dpp v16, v16, v16 row_half_mirror row_mask:0xf bank_mask:0xf bound_ctrl:1
	s_nop 1
	v_add_f32_dpp v16, v16, v16 row_mirror row_mask:0xf bank_mask:0xf bound_ctrl:1
	s_nop 0
	v_readlane_b32 s2, v16, 16
	v_readlane_b32 s10, v16, 48
	v_readlane_b32 s0, v16, 0
	v_readlane_b32 s1, v16, 32
	v_mov_b32_e32 v16, s2
	v_mov_b32_e32 v17, s10
	v_pk_add_f32 v[16:17], s[0:1], v[16:17]
	s_mov_b32 s0, 0x800000
	v_add_f32_e32 v16, v16, v17
	v_fmamk_f32 v16, v16, 0x3a800000, v116
	v_cmp_gt_f32_e32 vcc, s0, v16
	v_mul_f32_e32 v17, 0x4b800000, v16
	s_nop 0
	v_cndmask_b32_e32 v16, v16, v17, vcc
	v_rsq_f32_e32 v54, v16
	ds_read_b128 v[16:19], v60 offset:53248
	s_waitcnt lgkmcnt(15)
	ds_read_b128 v[20:23], v60 offset:57344
	s_waitcnt lgkmcnt(15)
	ds_read_b128 v[24:27], v60 offset:61440
	s_waitcnt lgkmcnt(15)
	v_mul_f32_e32 v55, 0x45800000, v54
	v_cndmask_b32_e32 v98, v54, v55, vcc
	v_pk_mul_f32 v[28:29], v[28:29], v[98:99] op_sel_hi:[1,0]
	v_pk_fma_f32 v[106:107], v[30:31], v[28:29], v[34:35]
	v_pk_mul_f32 v[28:29], v[126:127], v[98:99] op_sel_hi:[1,0]
	s_waitcnt lgkmcnt(2)
	v_mul_f32_e32 v17, v107, v17
	v_pk_fma_f32 v[104:105], v[32:33], v[28:29], v[36:37]
	v_cvt_pk_bf16_f32 v28, v106, v107
	v_cvt_pk_bf16_f32 v29, v104, v105
	global_store_dwordx2 v[86:87], v[28:29], off offset:-1024
	v_mul_f32_e32 v54, v39, v107
	v_fmac_f32_e32 v54, v38, v106
	ds_read_b128 v[32:35], v234 offset:1024
	ds_read_b128 v[36:39], v234 offset:5120
	v_fmac_f32_e32 v54, v104, v40
	v_fmac_f32_e32 v54, v105, v41
	v_mul_f32_e32 v55, v107, v43
	v_fmac_f32_e32 v55, v106, v42
	v_fmac_f32_e32 v55, v104, v44
	v_fmac_f32_e32 v55, v105, v45
	v_mul_f32_e32 v28, v107, v47
	v_fmac_f32_e32 v28, v106, v46
	v_fmac_f32_e32 v28, v104, v48
	v_fmac_f32_e32 v28, v105, v49
	v_add_f32_e32 v46, 0, v28
	v_mul_f32_e32 v45, v107, v51
	v_fmac_f32_e32 v45, v106, v50
	v_fmac_f32_e32 v45, v104, v52
	v_fmac_f32_e32 v45, v105, v53
	v_mul_f32_e32 v44, v107, v109
	v_fmac_f32_e32 v44, v106, v108
	v_fmac_f32_e32 v44, v104, v110
	v_fmac_f32_e32 v44, v105, v111
	v_mul_f32_e32 v53, v107, v123
	v_fmac_f32_e32 v53, v106, v122
	v_fmac_f32_e32 v53, v104, v124
	v_fmac_f32_e32 v53, v105, v125
	v_mul_f32_e32 v52, v107, v131
	v_fmac_f32_e32 v52, v106, v130
	v_fmac_f32_e32 v52, v104, v132
	v_fmac_f32_e32 v52, v105, v133
	v_mul_f32_e32 v51, v107, v135
	v_fmac_f32_e32 v51, v106, v134
	v_fmac_f32_e32 v51, v104, v136
	v_fmac_f32_e32 v51, v105, v137
	v_mul_f32_e32 v50, v107, v139
	v_fmac_f32_e32 v50, v106, v138
	v_fmac_f32_e32 v50, v104, v140
	v_fmac_f32_e32 v50, v105, v141
	v_mul_f32_e32 v49, v107, v143
	v_fmac_f32_e32 v49, v106, v142
	v_fmac_f32_e32 v49, v104, v144
	v_fmac_f32_e32 v49, v105, v145
	v_mul_f32_e32 v48, v107, v147
	v_fmac_f32_e32 v48, v106, v146
	v_fmac_f32_e32 v48, v104, v148
	v_fmac_f32_e32 v48, v105, v149
	v_mul_f32_e32 v131, v107, v151
	v_fmac_f32_e32 v17, v106, v16
	s_waitcnt lgkmcnt(3)
	v_mul_f32_e32 v122, v107, v21
	v_fmac_f32_e32 v131, v106, v150
	v_fmac_f32_e32 v122, v106, v20
	v_fmac_f32_e32 v131, v104, v152
	v_fmac_f32_e32 v122, v104, v22
	v_fmac_f32_e32 v131, v105, v153
	v_fmac_f32_e32 v122, v105, v23
	v_mul_f32_e32 v125, v107, v155
	s_waitcnt lgkmcnt(2)
	v_mul_f32_e32 v123, v107, v25
	v_fmac_f32_e32 v125, v106, v154
	v_fmac_f32_e32 v123, v106, v24
	v_fmac_f32_e32 v125, v104, v156
	v_fmac_f32_e32 v17, v104, v18
	v_fmac_f32_e32 v123, v104, v26
	v_fmac_f32_e32 v125, v105, v157
	v_fmac_f32_e32 v17, v105, v19
	v_fmac_f32_e32 v123, v105, v27
	v_pk_mul_f32 v[40:41], v[158:159], v[98:99] op_sel_hi:[1,0]
	v_add_f32_e32 v124, 0, v17
	s_waitcnt lgkmcnt(0)
	v_pk_fma_f32 v[108:109], v[40:41], v[32:33], v[36:37]
	ds_read_b128 v[40:43], v60 offset:1024
	ds_read_b128 v[134:137], v60 offset:21504
	v_pk_mul_f32 v[32:33], v[160:161], v[98:99] op_sel_hi:[1,0]
	ds_read_b128 v[142:145], v60 offset:29696
	v_pk_fma_f32 v[110:111], v[32:33], v[34:35], v[38:39]
	s_waitcnt lgkmcnt(2)
	v_fma_f32 v126, v109, v41, v54
	v_cvt_pk_bf16_f32 v32, v108, v109
	v_cvt_pk_bf16_f32 v33, v110, v111
	v_fmac_f32_e32 v126, v108, v40
	global_store_dwordx2 v[86:87], v[32:33], off offset:-512
	ds_read_b128 v[32:35], v60 offset:5120
	v_fmac_f32_e32 v126, v110, v42
	v_fmac_f32_e32 v126, v111, v43
	s_waitcnt lgkmcnt(2)
	v_fma_f32 v133, v109, v135, v53
	s_waitcnt lgkmcnt(1)
	v_fma_f32 v135, v109, v143, v51
	v_fmac_f32_e32 v135, v108, v142
	v_fmac_f32_e32 v135, v110, v144
	v_fmac_f32_e32 v135, v111, v145
	ds_read_b128 v[144:147], v60 offset:50176
	s_waitcnt lgkmcnt(1)
	v_fma_f32 v127, v109, v33, v55
	v_fmac_f32_e32 v127, v108, v32
	v_fmac_f32_e32 v127, v110, v34
	v_fmac_f32_e32 v127, v111, v35
	ds_read_b128 v[36:39], v60 offset:9216
	ds_read_b128 v[32:35], v60 offset:13312
	ds_read_b128 v[40:43], v60 offset:17408
	ds_read_b128 v[138:141], v60 offset:25600
	v_fmac_f32_e32 v133, v108, v134
	v_fmac_f32_e32 v133, v110, v136
	s_waitcnt lgkmcnt(3)
	v_fma_f32 v129, v109, v37, v46
	s_waitcnt lgkmcnt(2)
	v_fma_f32 v130, v109, v33, v45
	v_fmac_f32_e32 v133, v111, v137
	v_fmac_f32_e32 v129, v108, v36
	v_fmac_f32_e32 v130, v108, v32
	s_waitcnt lgkmcnt(0)
	v_fma_f32 v134, v109, v139, v52
	v_fmac_f32_e32 v129, v110, v38
	v_fmac_f32_e32 v130, v110, v34
	v_fma_f32 v132, v109, v41, v44
	v_fmac_f32_e32 v134, v108, v138
	v_fmac_f32_e32 v129, v111, v39
	v_fmac_f32_e32 v130, v111, v35
	v_fmac_f32_e32 v132, v108, v40
	v_fmac_f32_e32 v134, v110, v140
	v_fmac_f32_e32 v132, v110, v42
	v_fmac_f32_e32 v134, v111, v141
	v_fmac_f32_e32 v132, v111, v43
	ds_read_b128 v[52:55], v60 offset:33792
	ds_read_b128 v[138:141], v60 offset:37888
	s_waitcnt lgkmcnt(1)
	v_fma_f32 v136, v109, v53, v50
	v_fmac_f32_e32 v136, v108, v52
	v_fmac_f32_e32 v136, v110, v54
	v_fmac_f32_e32 v136, v111, v55
	ds_read_b128 v[50:53], v60 offset:41984
	s_waitcnt lgkmcnt(1)
	v_fma_f32 v137, v109, v139, v49
	v_fmac_f32_e32 v137, v108, v138
	v_fmac_f32_e32 v137, v110, v140
	v_fmac_f32_e32 v137, v111, v141
	ds_read_b128 v[140:143], v60 offset:46080
	s_waitcnt lgkmcnt(1)
	v_fma_f32 v138, v109, v51, v48
	v_fmac_f32_e32 v138, v108, v50
	v_fmac_f32_e32 v138, v110, v52
	v_fmac_f32_e32 v138, v111, v53
	ds_read_b128 v[48:51], v234 offset:2048
	ds_read_b128 v[52:55], v234 offset:6144
	s_waitcnt lgkmcnt(2)
	v_fma_f32 v131, v109, v141, v131
	v_fmac_f32_e32 v131, v108, v140
	v_fmac_f32_e32 v131, v110, v142
	v_fmac_f32_e32 v131, v111, v143
	ds_read_b128 v[140:143], v60 offset:54272
	v_fma_f32 v139, v109, v145, v125
	v_fmac_f32_e32 v139, v108, v144
	v_fmac_f32_e32 v139, v110, v146
	v_fmac_f32_e32 v139, v111, v147
	ds_read_b128 v[144:147], v60 offset:58368
	s_waitcnt lgkmcnt(1)
	v_fma_f32 v148, v109, v141, v124
	v_fmac_f32_e32 v148, v108, v140
	v_fmac_f32_e32 v148, v110, v142
	v_fmac_f32_e32 v148, v111, v143
	ds_read_b128 v[140:143], v60 offset:62464
	s_waitcnt lgkmcnt(1)
	v_mul_f32_e32 v124, v109, v145
	v_fmac_f32_e32 v124, v108, v144
	v_fmac_f32_e32 v124, v110, v146
	v_fmac_f32_e32 v124, v111, v147
	v_add_f32_e32 v144, v122, v124
	s_waitcnt lgkmcnt(0)
	v_mul_f32_e32 v122, v109, v141
	v_fmac_f32_e32 v122, v108, v140
	v_fmac_f32_e32 v122, v110, v142
	v_fmac_f32_e32 v122, v111, v143
	v_add_f32_e32 v142, v123, v122
	v_mov_b32_e32 v122, v106
	v_mov_b32_e32 v123, v108
	v_mov_b32_e32 v108, v107
	v_mov_b32_e32 v106, v186
	v_mov_b32_e32 v124, v182
	v_mov_b32_e32 v140, v190
	v_mov_b32_e32 v125, v198
	v_mov_b32_e32 v107, v202
	v_pk_mul_f32 v[106:107], v[108:109], v[106:107]
	v_mov_b32_e32 v36, v187
	v_pk_fma_f32 v[106:107], v[122:123], v[124:125], v[106:107]
	v_mov_b32_e32 v124, v104
	v_mov_b32_e32 v125, v110
	v_mov_b32_e32 v110, v105
	v_mov_b32_e32 v104, v194
	v_mov_b32_e32 v141, v206
	v_pk_fma_f32 v[106:107], v[124:125], v[140:141], v[106:107]
	v_mov_b32_e32 v105, v210
	v_mov_b32_e32 v32, v183
	v_mov_b32_e32 v37, v203
	v_pk_mul_f32 v[24:25], v[108:109], v[36:37]
	v_pk_fma_f32 v[104:105], v[110:111], v[104:105], v[106:107]
	v_mov_b32_e32 v33, v199
	v_pk_fma_f32 v[24:25], v[122:123], v[32:33], v[24:25]
	v_mov_b32_e32 v40, v191
	v_add_f32_e32 v16, 0, v104
	v_mov_b32_e32 v41, v207
	v_pk_fma_f32 v[20:21], v[124:125], v[40:41], v[24:25]
	v_mov_b32_e32 v44, v195
	v_add_f32_e32 v107, v16, v105
	v_mov_b32_e32 v45, v211
	v_pk_fma_f32 v[16:17], v[110:111], v[44:45], v[20:21]
	v_mov_b32_e32 v20, v188
	v_add_f32_e32 v16, 0, v16
	v_mov_b32_e32 v21, v204
	v_add_f32_e32 v105, v16, v17
	v_mov_b32_e32 v16, v184
	v_mov_b32_e32 v17, v200
	v_pk_mul_f32 v[20:21], v[108:109], v[20:21]
	v_mov_b32_e32 v38, v189
	v_pk_fma_f32 v[16:17], v[122:123], v[16:17], v[20:21]
	v_mov_b32_e32 v20, v192
	v_mov_b32_e32 v21, v208
	v_pk_fma_f32 v[16:17], v[124:125], v[20:21], v[16:17]
	v_mov_b32_e32 v20, v196
	v_mov_b32_e32 v21, v212
	v_pk_fma_f32 v[16:17], v[110:111], v[20:21], v[16:17]
	v_mov_b32_e32 v34, v185
	v_add_f32_e32 v16, 0, v16
	v_add_f32_e32 v106, v16, v17
	v_mov_b32_e32 v39, v205
	v_pk_mul_f32 v[16:17], v[108:109], v[38:39]
	v_mov_b32_e32 v42, v193
	v_mov_b32_e32 v35, v201
	v_pk_fma_f32 v[16:17], v[122:123], v[34:35], v[16:17]
	v_mov_b32_e32 v46, v197
	v_mov_b32_e32 v43, v209
	v_pk_fma_f32 v[16:17], v[124:125], v[42:43], v[16:17]
	v_pk_mul_f32 v[20:21], v[102:103], v[98:99] op_sel_hi:[1,0]
	v_mov_b32_e32 v47, v213
	v_pk_fma_f32 v[16:17], v[110:111], v[46:47], v[16:17]
	v_pk_fma_f32 v[50:51], v[20:21], v[50:51], v[54:55]
	v_add_f32_e32 v16, 0, v16
	v_add_f32_e32 v104, v16, v17
	v_pk_mul_f32 v[16:17], v[100:101], v[98:99] op_sel_hi:[1,0]
	v_cvt_pk_bf16_f32 v21, v50, v51
	v_pk_fma_f32 v[48:49], v[16:17], v[48:49], v[52:53]
	ds_read_b128 v[16:19], v60 offset:2048
	v_cvt_pk_bf16_f32 v20, v48, v49
	global_store_dwordx2 v[86:87], v[20:21], off
	ds_read_b128 v[20:23], v60 offset:6144
	v_pk_mul_f32 v[46:47], v[94:95], v[98:99] op_sel_hi:[1,0]
	s_waitcnt lgkmcnt(1)
	v_fma_f32 v42, v49, v17, v126
	v_fmac_f32_e32 v42, v48, v16
	v_fmac_f32_e32 v42, v50, v18
	v_fmac_f32_e32 v42, v51, v19
	ds_read_b128 v[16:19], v60 offset:10240
	s_waitcnt lgkmcnt(1)
	v_fma_f32 v41, v49, v21, v127
	v_fmac_f32_e32 v41, v48, v20
	v_fmac_f32_e32 v41, v50, v22
	v_fmac_f32_e32 v41, v51, v23
	ds_read_b128 v[20:23], v60 offset:14336
	s_waitcnt lgkmcnt(1)
	v_fma_f32 v40, v49, v17, v129
	v_fmac_f32_e32 v40, v48, v16
	v_fmac_f32_e32 v40, v50, v18
	v_fmac_f32_e32 v40, v51, v19
	ds_read_b128 v[16:19], v60 offset:18432
	ds_read_b128 v[32:35], v234 offset:3072
	ds_read_b128 v[36:39], v234 offset:7168
	s_waitcnt lgkmcnt(3)
	v_fma_f32 v45, v49, v21, v130
	v_fmac_f32_e32 v45, v48, v20
	v_fmac_f32_e32 v45, v50, v22
	v_fmac_f32_e32 v45, v51, v23
	ds_read_b128 v[20:23], v60 offset:22528
	s_waitcnt lgkmcnt(3)
	v_fma_f32 v44, v49, v17, v132
	v_fmac_f32_e32 v44, v48, v16
	v_fmac_f32_e32 v44, v50, v18
	v_fmac_f32_e32 v44, v51, v19
	ds_read_b128 v[16:19], v60 offset:26624
	s_waitcnt lgkmcnt(1)
	v_fma_f32 v124, v49, v21, v133
	v_fmac_f32_e32 v124, v48, v20
	v_fmac_f32_e32 v124, v50, v22
	v_fmac_f32_e32 v124, v51, v23
	ds_read_b128 v[20:23], v60 offset:30720
	s_waitcnt lgkmcnt(1)
	v_fma_f32 v123, v49, v17, v134
	v_fmac_f32_e32 v123, v48, v16
	v_fmac_f32_e32 v123, v50, v18
	v_fmac_f32_e32 v123, v51, v19
	s_waitcnt lgkmcnt(0)
	v_fma_f32 v122, v49, v21, v135
	v_fmac_f32_e32 v122, v48, v20
	v_fmac_f32_e32 v122, v50, v22
	ds_read_b128 v[16:19], v60 offset:34816
	v_fmac_f32_e32 v122, v51, v23
	ds_read_b128 v[20:23], v60 offset:38912
	s_waitcnt lgkmcnt(1)
	v_fma_f32 v111, v49, v17, v136
	v_fmac_f32_e32 v111, v48, v16
	v_fmac_f32_e32 v111, v50, v18
	s_waitcnt lgkmcnt(0)
	v_fma_f32 v110, v49, v21, v137
	v_fmac_f32_e32 v110, v48, v20
	v_fmac_f32_e32 v111, v51, v19
	v_fmac_f32_e32 v110, v50, v22
	ds_read_b128 v[16:19], v60 offset:43008
	v_fmac_f32_e32 v110, v51, v23
	ds_read_b128 v[20:23], v60 offset:47104
	s_waitcnt lgkmcnt(1)
	v_fma_f32 v109, v49, v17, v138
	v_fmac_f32_e32 v109, v48, v16
	v_fmac_f32_e32 v109, v50, v18
	s_waitcnt lgkmcnt(0)
	v_fma_f32 v108, v49, v21, v131
	v_fmac_f32_e32 v108, v48, v20
	v_fmac_f32_e32 v109, v51, v19
	v_fmac_f32_e32 v108, v50, v22
	ds_read_b128 v[16:19], v60 offset:51200
	v_fmac_f32_e32 v108, v51, v23
	ds_read_b128 v[20:23], v60 offset:55296
	s_waitcnt lgkmcnt(1)
	v_fma_f32 v103, v49, v17, v139
	v_fmac_f32_e32 v103, v48, v16
	v_fmac_f32_e32 v103, v50, v18
	s_waitcnt lgkmcnt(0)
	v_fma_f32 v102, v49, v21, v148
	v_fmac_f32_e32 v102, v48, v20
	v_fmac_f32_e32 v103, v51, v19
	v_fmac_f32_e32 v102, v50, v22
	ds_read_b128 v[16:19], v60 offset:59392
	v_fmac_f32_e32 v102, v51, v23
	ds_read_b128 v[20:23], v60 offset:63488
	s_waitcnt lgkmcnt(1)
	v_fma_f32 v100, v49, v17, v144
	v_fmac_f32_e32 v100, v48, v16
	v_fmac_f32_e32 v100, v50, v18
	s_waitcnt lgkmcnt(0)
	v_fma_f32 v101, v49, v21, v142
	v_fmac_f32_e32 v101, v48, v20
	v_fmac_f32_e32 v101, v50, v22
	v_fmac_f32_e32 v100, v51, v19
	v_fmac_f32_e32 v101, v51, v23
	v_pk_fma_f32 v[52:53], v[46:47], v[32:33], v[36:37]
	v_pk_mul_f32 v[32:33], v[96:97], v[98:99] op_sel_hi:[1,0]
	ds_read_b128 v[94:97], v60 offset:3072
	v_pk_fma_f32 v[54:55], v[32:33], v[34:35], v[38:39]
	v_cvt_pk_bf16_f32 v32, v52, v53
	v_cvt_pk_bf16_f32 v33, v54, v55
	global_store_dwordx2 v[86:87], v[32:33], off offset:512
	ds_read_b128 v[32:35], v60 offset:7168
	s_waitcnt lgkmcnt(1)
	v_mul_f32_e32 v36, v53, v95
	v_fmac_f32_e32 v36, v52, v94
	v_fmac_f32_e32 v36, v54, v96
	v_fmac_f32_e32 v36, v55, v97
	v_add_f32_e32 v94, v42, v36
	ds_read_b128 v[36:39], v60 offset:11264
	ds_read_b128 v[130:133], v60 offset:15360
	s_waitcnt lgkmcnt(2)
	v_fma_f32 v95, v53, v33, v41
	v_fmac_f32_e32 v95, v52, v32
	v_fmac_f32_e32 v95, v54, v34
	s_waitcnt lgkmcnt(1)
	v_fma_f32 v96, v53, v37, v40
	v_fmac_f32_e32 v96, v52, v36
	v_fmac_f32_e32 v96, v54, v38
	v_fmac_f32_e32 v95, v55, v35
	v_fmac_f32_e32 v96, v55, v39
	ds_read_b128 v[40:43], v60 offset:19456
	s_waitcnt lgkmcnt(1)
	v_fma_f32 v97, v53, v131, v45
	v_fmac_f32_e32 v97, v52, v130
	v_fmac_f32_e32 v97, v54, v132
	v_fmac_f32_e32 v97, v55, v133
	ds_read_b128 v[130:133], v60 offset:23552
	s_waitcnt lgkmcnt(1)
	v_fma_f32 v125, v53, v41, v44
	v_fmac_f32_e32 v125, v52, v40
	v_fmac_f32_e32 v125, v54, v42
	v_fmac_f32_e32 v125, v55, v43
	ds_read_b128 v[134:137], v60 offset:27648
	s_waitcnt lgkmcnt(1)
	v_fma_f32 v124, v53, v131, v124
	v_fmac_f32_e32 v124, v52, v130
	v_fmac_f32_e32 v124, v54, v132
	v_fmac_f32_e32 v124, v55, v133
	ds_read_b128 v[130:133], v60 offset:31744
	s_waitcnt lgkmcnt(1)
	v_fma_f32 v98, v53, v135, v123
	v_fmac_f32_e32 v98, v52, v134
	v_fmac_f32_e32 v98, v54, v136
	v_fmac_f32_e32 v98, v55, v137
	ds_read_b128 v[134:137], v60 offset:35840
	s_waitcnt lgkmcnt(1)
	v_fma_f32 v122, v53, v131, v122
	v_fmac_f32_e32 v122, v52, v130
	v_fmac_f32_e32 v122, v54, v132
	v_fmac_f32_e32 v122, v55, v133
	ds_read_b128 v[130:133], v60 offset:39936
	s_waitcnt lgkmcnt(1)
	v_fma_f32 v111, v53, v135, v111
	v_fmac_f32_e32 v111, v52, v134
	v_fmac_f32_e32 v111, v54, v136
	v_fmac_f32_e32 v111, v55, v137
	ds_read_b128 v[134:137], v60 offset:44032
	s_waitcnt lgkmcnt(1)
	v_fma_f32 v110, v53, v131, v110
	v_fmac_f32_e32 v110, v52, v130
	v_fmac_f32_e32 v110, v54, v132
	v_fmac_f32_e32 v110, v55, v133
	ds_read_b128 v[130:133], v60 offset:48128
	s_waitcnt lgkmcnt(1)
	v_fma_f32 v109, v53, v135, v109
	v_fmac_f32_e32 v109, v52, v134
	v_fmac_f32_e32 v109, v54, v136
	v_fmac_f32_e32 v109, v55, v137
	ds_read_b128 v[134:137], v60 offset:52224
	s_waitcnt lgkmcnt(1)
	v_fma_f32 v108, v53, v131, v108
	v_fmac_f32_e32 v108, v52, v130
	v_fmac_f32_e32 v108, v54, v132
	v_fmac_f32_e32 v108, v55, v133
	ds_read_b128 v[130:133], v60 offset:56320
	s_waitcnt lgkmcnt(1)
	v_fma_f32 v103, v53, v135, v103
	v_fmac_f32_e32 v103, v52, v134
	v_fmac_f32_e32 v103, v54, v136
	v_fmac_f32_e32 v103, v55, v137
	ds_read_b128 v[134:137], v60 offset:60416
	s_waitcnt lgkmcnt(1)
	v_fma_f32 v102, v53, v131, v102
	v_fmac_f32_e32 v102, v52, v130
	v_fmac_f32_e32 v102, v54, v132
	v_fmac_f32_e32 v102, v55, v133
	ds_read_b128 v[130:133], v60 offset:64512
	s_waitcnt lgkmcnt(1)
	v_fma_f32 v123, v53, v135, v100
	v_fmac_f32_e32 v123, v52, v134
	v_fmac_f32_e32 v123, v54, v136
	v_fmac_f32_e32 v123, v55, v137
	s_waitcnt lgkmcnt(0)
	v_fma_f32 v129, v53, v131, v101
	v_fmac_f32_e32 v129, v52, v130
	v_fmac_f32_e32 v129, v54, v132
	v_fmac_f32_e32 v129, v55, v133
	v_mov_b32_e32 v100, v48
	v_mov_b32_e32 v101, v52
	v_mov_b32_e32 v52, v49
	v_mov_b32_e32 v48, v218
	v_mov_b32_e32 v126, v214
	v_mov_b32_e32 v130, v222
	v_mov_b32_e32 v127, v230
	v_mov_b32_e32 v49, v238
	v_pk_mul_f32 v[48:49], v[52:53], v[48:49]
	v_mov_b32_e32 v36, v219
	v_pk_fma_f32 v[48:49], v[100:101], v[126:127], v[48:49]
	v_mov_b32_e32 v126, v50
	v_mov_b32_e32 v127, v54
	v_mov_b32_e32 v131, v242
	v_pk_fma_f32 v[48:49], v[126:127], v[130:131], v[48:49]
	v_mov_b32_e32 v54, v51
	v_mov_b32_e32 v50, v226
	v_mov_b32_e32 v51, v246
	v_mov_b32_e32 v32, v215
	v_mov_b32_e32 v37, v239
	v_pk_mul_f32 v[24:25], v[52:53], v[36:37]
	v_pk_fma_f32 v[48:49], v[54:55], v[50:51], v[48:49]
	v_mov_b32_e32 v33, v231
	v_pk_fma_f32 v[24:25], v[100:101], v[32:33], v[24:25]
	v_mov_b32_e32 v40, v223
	v_add_f32_e32 v16, v107, v48
	v_mov_b32_e32 v41, v243
	v_pk_fma_f32 v[20:21], v[126:127], v[40:41], v[24:25]
	v_mov_b32_e32 v44, v227
	v_add_f32_e32 v28, v16, v49
	v_mov_b32_e32 v45, v247
	v_pk_fma_f32 v[16:17], v[54:55], v[44:45], v[20:21]
	v_mov_b32_e32 v20, v220
	v_add_f32_e32 v16, v105, v16
	v_mov_b32_e32 v21, v240
	v_add_f32_e32 v24, v16, v17
	v_mov_b32_e32 v16, v216
	v_mov_b32_e32 v17, v232
	v_pk_mul_f32 v[20:21], v[52:53], v[20:21]
	v_mov_b32_e32 v38, v221
	v_pk_fma_f32 v[16:17], v[100:101], v[16:17], v[20:21]
	v_mov_b32_e32 v20, v224
	v_mov_b32_e32 v21, v244
	v_pk_fma_f32 v[16:17], v[126:127], v[20:21], v[16:17]
	v_mov_b32_e32 v20, v228
	v_mov_b32_e32 v21, v248
	v_pk_fma_f32 v[16:17], v[54:55], v[20:21], v[16:17]
	v_mov_b32_e32 v34, v217
	v_add_f32_e32 v16, v106, v16
	v_add_f32_e32 v20, v16, v17
	v_mov_b32_e32 v39, v241
	v_pk_mul_f32 v[16:17], v[52:53], v[38:39]
	v_mov_b32_e32 v42, v225
	v_mov_b32_e32 v35, v233
	v_pk_fma_f32 v[16:17], v[100:101], v[34:35], v[16:17]
	v_mov_b32_e32 v46, v229
	v_mov_b32_e32 v43, v245
	v_pk_fma_f32 v[16:17], v[126:127], v[42:43], v[16:17]
	v_mov_b32_e32 v47, v249
	v_pk_fma_f32 v[16:17], v[54:55], v[46:47], v[16:17]
	v_add_f32_e32 v16, v104, v16
	v_add_f32_e32 v22, v16, v17
	v_add_f32_dpp v250, v24, v24 row_mirror row_mask:0xf bank_mask:0xf bound_ctrl:1
	v_add_f32_dpp v250, v20, v20 row_mirror row_mask:0xf bank_mask:0xc bound_ctrl:1
	v_add_f32_dpp v251, v28, v28 row_mirror row_mask:0xf bank_mask:0xf bound_ctrl:1
	v_add_f32_dpp v251, v22, v22 row_mirror row_mask:0xf bank_mask:0xc bound_ctrl:1
	v_add_f32_dpp v250, v250, v250 row_half_mirror row_mask:0xf bank_mask:0xf bound_ctrl:1
	s_nop 0
	v_add_f32_dpp v250, v251, v251 row_half_mirror row_mask:0xf bank_mask:0xa bound_ctrl:1
	s_nop 1
	v_add_f32_dpp v250, v250, v250 quad_perm:[1,0,3,2] row_mask:0xf bank_mask:0xf bound_ctrl:1
	s_nop 1
	v_add_f32_dpp v250, v250, v250 quad_perm:[2,3,0,1] row_mask:0xf bank_mask:0xf bound_ctrl:1
	s_nop 0
	v_readlane_b32 s2, v250, 20
	v_readlane_b32 s10, v250, 52
	v_readlane_b32 s0, v250, 4
	v_readlane_b32 s1, v250, 36
	v_mov_b32_e32 v16, s2
	v_mov_b32_e32 v17, s10
	v_readlane_b32 s2, v250, 16
	v_readlane_b32 s10, v250, 48
	v_pk_add_f32 v[16:17], s[0:1], v[16:17]
	v_readlane_b32 s0, v250, 0
	v_readlane_b32 s1, v250, 32
	v_mov_b32_e32 v18, s2
	v_mov_b32_e32 v19, s10
	v_readlane_b32 s2, v250, 24
	v_readlane_b32 s10, v250, 56
	v_pk_add_f32 v[18:19], s[0:1], v[18:19]
	v_readlane_b32 s0, v250, 8
	v_readlane_b32 s1, v250, 40
	v_mov_b32_e32 v20, s2
	v_mov_b32_e32 v21, s10
	v_pk_add_f32 v[20:21], s[0:1], v[20:21]
	v_mov_b32_e32 v25, v18
	v_add_f32_e32 v26, v20, v21
	v_mov_b32_e32 v18, v17
	v_readlane_b32 s2, v250, 28
	v_readlane_b32 s10, v250, 60
	v_readlane_b32 s0, v250, 12
	v_readlane_b32 s1, v250, 44
	v_mov_b32_e32 v20, s2
	v_mov_b32_e32 v21, s10
	v_pk_add_f32 v[20:21], s[0:1], v[20:21]
	v_add_f32_e32 v27, v20, v21
	v_mov_b32_e32 v24, v16
	v_pk_add_f32 v[16:17], v[24:25], v[18:19]
	v_mov_b32_e32 v20, v178
	v_mov_b32_e32 v21, v179
	v_mov_b32_e32 v22, v180
	v_mov_b32_e32 v23, v181
	v_add_f32_e32 v19, v26, v22
	v_pk_add_f32 v[16:17], v[16:17], v[20:21]
	v_add_f32_e32 v18, v27, v23
	v_cmp_gt_f32_e32 vcc, v17, v16
	v_mov_b32_e32 v22, 0
	s_nop 0
	v_cndmask_b32_e32 v20, v16, v17, vcc
	v_cmp_gt_f32_e64 s[12:13], v19, v20
	v_cndmask_b32_e64 v21, 0, 1, vcc
	s_and_b64 s[10:11], s[12:13], exec
	v_cndmask_b32_e64 v20, v20, v19, s[12:13]
	v_cmp_ngt_f32_e64 s[0:1], v18, v20
	v_readfirstlane_b32 s2, v21
	s_cselect_b32 s2, 2, s2
	s_and_b64 s[10:11], s[0:1], exec
	s_cselect_b32 s2, s2, 3
	s_cmp_eq_u32 s2, 0
	s_cbranch_scc0 .Lmy_rselb_1
	v_add_f32_dpp v94, v94, v94 row_mirror row_mask:0xf bank_mask:0xf bound_ctrl:1
	v_add_f32_dpp v94, v95, v95 row_mirror row_mask:0xf bank_mask:0xc bound_ctrl:1
	v_add_f32_dpp v96, v96, v96 row_mirror row_mask:0xf bank_mask:0xf bound_ctrl:1
	v_add_f32_dpp v96, v97, v97 row_mirror row_mask:0xf bank_mask:0xc bound_ctrl:1
	v_add_f32_dpp v94, v94, v94 row_half_mirror row_mask:0xf bank_mask:0xf bound_ctrl:1
	s_nop 0
	v_add_f32_dpp v94, v96, v96 row_half_mirror row_mask:0xf bank_mask:0xa bound_ctrl:1
	s_nop 1
	v_add_f32_dpp v94, v94, v94 quad_perm:[1,0,3,2] row_mask:0xf bank_mask:0xf bound_ctrl:1
	s_nop 1
	v_add_f32_dpp v94, v94, v94 quad_perm:[2,3,0,1] row_mask:0xf bank_mask:0xf bound_ctrl:1
	s_nop 0
	v_readlane_b32 s14, v94, 0
	v_readlane_b32 s94, v94, 16
	v_readlane_b32 s15, v94, 32
	v_readlane_b32 s95, v94, 48
	v_readlane_b32 s87, v94, 8
	v_readlane_b32 s91, v94, 24
	v_readlane_b32 s90, v94, 40
	v_readlane_b32 s92, v94, 56
	v_readlane_b32 s65, v94, 4
	v_readlane_b32 s75, v94, 20
	v_readlane_b32 s66, v94, 36
	v_readlane_b32 s78, v94, 52
	v_readlane_b32 s51, v94, 12
	v_readlane_b32 s53, v94, 28
	v_readlane_b32 s52, v94, 44
	v_readlane_b32 s54, v94, 60
	s_branch .Lmy_rselb_end
.Lmy_rselb_1:
	s_cmp_eq_u32 s2, 1
	s_cbranch_scc0 .Lmy_rselb_2
	v_add_f32_dpp v125, v125, v125 row_mirror row_mask:0xf bank_mask:0xf bound_ctrl:1
	v_add_f32_dpp v125, v124, v124 row_mirror row_mask:0xf bank_mask:0xc bound_ctrl:1
	v_add_f32_dpp v98, v98, v98 row_mirror row_mask:0xf bank_mask:0xf bound_ctrl:1
	v_add_f32_dpp v98, v122, v122 row_mirror row_mask:0xf bank_mask:0xc bound_ctrl:1
	v_add_f32_dpp v125, v125, v125 row_half_mirror row_mask:0xf bank_mask:0xf bound_ctrl:1
	s_nop 0
	v_add_f32_dpp v125, v98, v98 row_half_mirror row_mask:0xf bank_mask:0xa bound_ctrl:1
	s_nop 1
	v_add_f32_dpp v125, v125, v125 quad_perm:[1,0,3,2] row_mask:0xf bank_mask:0xf bound_ctrl:1
	s_nop 1
	v_add_f32_dpp v125, v125, v125 quad_perm:[2,3,0,1] row_mask:0xf bank_mask:0xf bound_ctrl:1
	s_nop 0
	v_readlane_b32 s35, v125, 0
	v_readlane_b32 s37, v125, 16
	v_readlane_b32 s36, v125, 32
	v_readlane_b32 s38, v125, 48
	v_readlane_b32 s23, v125, 8
	v_readlane_b32 s27, v125, 24
	v_readlane_b32 s26, v125, 40
	v_readlane_b32 s93, v125, 56
	v_readlane_b32 s81, v125, 4
	v_readlane_b32 s83, v125, 20
	v_readlane_b32 s82, v125, 36
	v_readlane_b32 s84, v125, 52
	v_readlane_b32 s63, v125, 12
	v_readlane_b32 s67, v125, 28
	v_readlane_b32 s64, v125, 44
	v_readlane_b32 s70, v125, 60
	s_branch .Lmy_rselb_end
.Lmy_rselb_2:
	s_cmp_eq_u32 s2, 2
	s_cbranch_scc0 .Lmy_rselb_3
	v_add_f32_dpp v111, v111, v111 row_mirror row_mask:0xf bank_mask:0xf bound_ctrl:1
	v_add_f32_dpp v111, v110, v110 row_mirror row_mask:0xf bank_mask:0xc bound_ctrl:1
	v_add_f32_dpp v109, v109, v109 row_mirror row_mask:0xf bank_mask:0xf bound_ctrl:1
	v_add_f32_dpp v109, v108, v108 row_mirror row_mask:0xf bank_mask:0xc bound_ctrl:1
	v_add_f32_dpp v111, v111, v111 row_half_mirror row_mask:0xf bank_mask:0xf bound_ctrl:1
	s_nop 0
	v_add_f32_dpp v111, v109, v109 row_half_mirror row_mask:0xf bank_mask:0xa bound_ctrl:1
	s_nop 1
	v_add_f32_dpp v111, v111, v111 quad_perm:[1,0,3,2] row_mask:0xf bank_mask:0xf bound_ctrl:1
	s_nop 1
	v_add_f32_dpp v111, v111, v111 quad_perm:[2,3,0,1] row_mask:0xf bank_mask:0xf bound_ctrl:1
	s_nop 0
	v_readlane_b32 s59, v111, 0
	v_readlane_b32 s61, v111, 16
	v_readlane_b32 s60, v111, 32
	v_readlane_b32 s62, v111, 48
	v_readlane_b32 s55, v111, 8
	v_readlane_b32 s57, v111, 24
	v_readlane_b32 s56, v111, 40
	v_readlane_b32 s58, v111, 56
	v_readlane_b32 s47, v111, 4
	v_readlane_b32 s49, v111, 20
	v_readlane_b32 s48, v111, 36
	v_readlane_b32 s50, v111, 52
	v_readlane_b32 s43, v111, 12
	v_readlane_b32 s45, v111, 28
	v_readlane_b32 s44, v111, 44
	v_readlane_b32 s46, v111, 60
	s_branch .Lmy_rselb_end
.Lmy_rselb_3:
	v_add_f32_dpp v103, v103, v103 row_mirror row_mask:0xf bank_mask:0xf bound_ctrl:1
	v_add_f32_dpp v103, v102, v102 row_mirror row_mask:0xf bank_mask:0xc bound_ctrl:1
	v_add_f32_dpp v123, v123, v123 row_mirror row_mask:0xf bank_mask:0xf bound_ctrl:1
	v_add_f32_dpp v123, v129, v129 row_mirror row_mask:0xf bank_mask:0xc bound_ctrl:1
	v_add_f32_dpp v103, v103, v103 row_half_mirror row_mask:0xf bank_mask:0xf bound_ctrl:1
	s_nop 0
	v_add_f32_dpp v103, v123, v123 row_half_mirror row_mask:0xf bank_mask:0xa bound_ctrl:1
	s_nop 1
	v_add_f32_dpp v103, v103, v103 quad_perm:[1,0,3,2] row_mask:0xf bank_mask:0xf bound_ctrl:1
	s_nop 1
	v_add_f32_dpp v103, v103, v103 quad_perm:[2,3,0,1] row_mask:0xf bank_mask:0xf bound_ctrl:1
	s_nop 0
	v_readlane_b32 s39, v103, 0
	v_readlane_b32 s41, v103, 16
	v_readlane_b32 s40, v103, 32
	v_readlane_b32 s42, v103, 48
	v_readlane_b32 s30, v103, 8
	v_readlane_b32 s33, v103, 24
	v_readlane_b32 s31, v103, 40
	v_readlane_b32 s34, v103, 56
	v_readlane_b32 s28, v103, 4
	v_readlane_b32 s29, v103, 20
	v_readlane_b32 s85, v103, 36
	v_readlane_b32 s86, v103, 52
	v_readlane_b32 s71, v103, 12
	v_readlane_b32 s79, v103, 28
	v_readlane_b32 s74, v103, 44
	v_readlane_b32 s80, v103, 60
.Lmy_rselb_end:
	s_cmp_eq_u32 s2, 0
	s_cselect_b64 s[24:25], -1, 0
	s_cmp_lg_u32 s2, 0
	v_mov_b32_e32 v21, 0
	v_cmp_gt_f32_e64 s[10:11], v18, v20
	s_waitcnt lgkmcnt(0)
	s_cbranch_scc0 .LBB0_1684
	v_cndmask_b32_e64 v23, 0, 1, s[24:25]
	v_cmp_ne_u32_e64 s[14:15], 1, v23
	s_andn2_b64 vcc, exec, s[24:25]
	s_cbranch_vccz .LBB0_1685
